# FFN_IN: next unit's first-tile fragment ds_reads hoisted above the SwiGLU epilogue (epilogue temps renamed out of the fragment registers)
# baseline (speedup 1.0000x reference)
.LBB0_146:
	s_waitcnt lgkmcnt(0)
	s_add_u32 s12, s4, 0xa400000
	s_addc_u32 s13, s5, 0
	s_lshl_b32 s4, s14, 5
	s_mov_b64 s[14:15], 0x80
	s_and_b32 s26, s4, 0x60
	s_add_i32 m0, s57, 0x18000
	v_lshl_add_u64 v[8:9], v[8:9], 0, s[14:15]
	s_lshl_b32 s25, s24, 13
	s_lshl_b32 s27, s26, 7
	s_waitcnt vmcnt(2)
	s_barrier
	global_load_lds_dwordx4 v[8:9], off
	v_lshl_add_u64 v[6:7], v[6:7], 0, s[14:15]
	s_add_i32 m0, s57, 0x1a000
	s_add_i32 s62, s57, 0x8000
	s_add_i32 s63, s57, 0xa000
	global_load_lds_dwordx4 v[6:7], off
	v_lshl_add_u64 v[2:3], v[2:3], 0, s[14:15]
	s_mov_b32 m0, s62
	s_add_u32 s4, s50, 0x40080
	global_load_lds_dwordx4 v[2:3], off
	v_lshl_add_u64 v[2:3], v[4:5], 0, s[14:15]
	s_mov_b32 m0, s63
	s_addc_u32 s5, s51, 0
	global_load_lds_dwordx4 v[2:3], off
	s_add_i32 m0, s57, 0x1c000
	v_lshl_add_u64 v[2:3], s[4:5], 0, v[134:135]
	global_load_lds_dwordx4 v[2:3], off
	v_lshl_add_u64 v[2:3], s[4:5], 0, v[130:131]
	s_add_i32 m0, s57, 0x1e000
	s_cmpk_lt_u32 s17, 0x100
	global_load_lds_dwordx4 v[2:3], off
	v_lshrrev_b32_e32 v3, 1, v10
	v_and_b32_e32 v3, 24, v3
	v_and_b32_e32 v2, 15, v10
	v_lshlrev_b32_e32 v4, 1, v3
	v_lshl_or_b32 v150, s24, 6, v2
	v_lshl_or_b32 v2, v2, 6, v4
	v_lshlrev_b32_e32 v4, 2, v10
	v_and_b32_e32 v4, 32, v4
	v_bitop3_b32 v5, v2, s25, v4 bitop3:0xde
	v_bitop3_b32 v151, v2, s27, v4 bitop3:0xde
	v_or_b32_e32 v2, s26, v3
	v_lshlrev_b32_e32 v3, 14, v15
	v_and_b32_e32 v3, 0xffff8000, v3
	v_lshl_add_u32 v3, v14, 11, v3
	v_and_b32_e32 v4, 1, v15
	v_lshl_or_b32 v3, v4, 6, v3
	v_lshl_add_u32 v140, v16, 1, v3
	v_lshlrev_b32_e32 v3, 14, v11
	v_and_b32_e32 v3, 0xffff8000, v3
	s_waitcnt vmcnt(6)
	v_lshl_add_u32 v3, v12, 11, v3
	v_and_b32_e32 v4, 1, v11
	s_sext_i32_i16 s47, s16
	s_cselect_b64 s[16:17], -1, 0
	v_lshl_or_b32 v3, v4, 6, v3
	s_add_i32 s66, 0, 0x10000
	s_add_i32 s67, 0, 0x14000
	v_or_b32_e32 v152, 16, v150
	v_or_b32_e32 v153, 32, v150
	v_or_b32_e32 v154, 48, v150
	s_ashr_i32 s64, s38, 31
	s_mov_b32 s65, s38
	v_mov_b32_e32 v141, v139
	v_lshl_add_u32 v142, v13, 1, v3
	v_mov_b32_e32 v143, v139
	v_mov_b64_e32 v[144:145], 0xb00
	v_mov_b64_e32 v[146:147], 0xaff
	v_add_u32_e32 v155, s66, v151
	v_add_u32_e32 v156, s67, v151
	v_add_u32_e32 v157, 0, v5
	v_mov_b32_e32 v158, 0x358637bd
	s_movk_i32 s68, 0x1600
	v_lshlrev_b32_e32 v138, 1, v2
	s_barrier
	ds_read_b128 v[160:163], v155
	ds_read_b128 v[164:167], v155 offset:1024
	ds_read_b128 v[168:171], v155 offset:2048
	ds_read_b128 v[172:175], v155 offset:3072
	ds_read_b128 v[176:179], v156
	ds_read_b128 v[180:183], v156 offset:1024
	ds_read_b128 v[184:187], v156 offset:2048
	ds_read_b128 v[188:191], v156 offset:3072
	ds_read_b128 v[192:195], v157
	ds_read_b128 v[196:199], v157 offset:1024
	ds_read_b128 v[200:203], v157 offset:2048
	ds_read_b128 v[204:207], v157 offset:3072
	ds_read_b128 v[208:211], v157 offset:4096
	ds_read_b128 v[212:215], v157 offset:5120
	ds_read_b128 v[216:219], v157 offset:6144
	ds_read_b128 v[220:223], v157 offset:7168
	s_branch .LBB0_149

.LBB0_151:
	s_ashr_i32 s27, s26, 31
	s_lshl_b64 s[42:43], s[26:27], 19
	s_add_u32 s42, s3, s42
	s_addc_u32 s43, s23, s43
	s_and_b64 s[44:45], s[4:5], exec
	s_cselect_b32 s27, s43, s49
	s_cselect_b32 s69, s42, s48
	s_ashr_i32 s25, s24, 31
	s_lshl_b64 s[44:45], s[24:25], 19
	s_add_u32 s44, s29, s44
	s_addc_u32 s45, s31, s45
	s_and_b64 s[52:53], s[4:5], exec
	s_cselect_b32 s25, s45, s51
	s_cselect_b32 s70, s44, s50
	s_add_u32 s48, s48, 0x40080
	s_addc_u32 s49, s49, 0
	s_add_u32 s71, s50, 0x100
	s_addc_u32 s72, s51, 0
	s_mov_b32 s73, -2
	s_add_u32 s50, s48, 0xfffc0080
	s_addc_u32 s51, s49, -1
	s_cmp_eq_u32 s73, 12
	s_cselect_b32 s53, s27, s51
	s_cselect_b32 s52, s69, s50
	s_cselect_b32 s51, s25, s72
	s_cselect_b32 s50, s70, s71
	v_lshl_add_u64 v[148:149], s[48:49], 0, v[140:141]
	s_add_i32 m0, s57, 0xc000
	global_load_lds_dwordx4 v[148:149], off
	v_lshl_add_u64 v[148:149], s[48:49], 0, v[142:143]
	s_add_i32 m0, s57, 0xe000
	s_nop 0
	global_load_lds_dwordx4 v[148:149], off
	s_waitcnt vmcnt(8)
	s_waitcnt lgkmcnt(0)
	s_setprio 1
	s_barrier
	v_mfma_f32_16x16x32_bf16 v[118:121], v[160:163], v[192:195], 0
	v_mfma_f32_16x16x32_bf16 v[114:117], v[168:171], v[192:195], 0
	v_mfma_f32_16x16x32_bf16 v[106:109], v[160:163], v[200:203], 0
	v_mfma_f32_16x16x32_bf16 v[98:101], v[168:171], v[200:203], 0
	v_mfma_f32_16x16x32_bf16 v[90:93], v[160:163], v[208:211], 0
	v_mfma_f32_16x16x32_bf16 v[82:85], v[168:171], v[208:211], 0
	v_mfma_f32_16x16x32_bf16 v[74:77], v[160:163], v[216:219], 0
	v_mfma_f32_16x16x32_bf16 v[66:69], v[168:171], v[216:219], 0
	v_mfma_f32_16x16x32_bf16 v[118:121], v[164:167], v[196:199], v[118:121]
	v_mfma_f32_16x16x32_bf16 v[114:117], v[172:175], v[196:199], v[114:117]
	v_mfma_f32_16x16x32_bf16 v[106:109], v[164:167], v[204:207], v[106:109]
	v_mfma_f32_16x16x32_bf16 v[98:101], v[172:175], v[204:207], v[98:101]
	v_mfma_f32_16x16x32_bf16 v[90:93], v[164:167], v[212:215], v[90:93]
	v_mfma_f32_16x16x32_bf16 v[82:85], v[172:175], v[212:215], v[82:85]
	v_mfma_f32_16x16x32_bf16 v[74:77], v[164:167], v[220:223], v[74:77]
	v_mfma_f32_16x16x32_bf16 v[66:69], v[172:175], v[220:223], v[66:69]
	s_setprio 0
	s_setprio 1
	v_mfma_f32_16x16x32_bf16 v[126:129], v[176:179], v[192:195], 0
	v_mfma_f32_16x16x32_bf16 v[122:125], v[184:187], v[192:195], 0
	v_mfma_f32_16x16x32_bf16 v[110:113], v[176:179], v[200:203], 0
	v_mfma_f32_16x16x32_bf16 v[102:105], v[184:187], v[200:203], 0
	v_mfma_f32_16x16x32_bf16 v[94:97], v[176:179], v[208:211], 0
	v_mfma_f32_16x16x32_bf16 v[86:89], v[184:187], v[208:211], 0
	v_mfma_f32_16x16x32_bf16 v[78:81], v[176:179], v[216:219], 0
	v_mfma_f32_16x16x32_bf16 v[70:73], v[184:187], v[216:219], 0
	v_mfma_f32_16x16x32_bf16 v[126:129], v[180:183], v[196:199], v[126:129]
	v_mfma_f32_16x16x32_bf16 v[122:125], v[188:191], v[196:199], v[122:125]
	v_mfma_f32_16x16x32_bf16 v[110:113], v[180:183], v[204:207], v[110:113]
	v_mfma_f32_16x16x32_bf16 v[102:105], v[188:191], v[204:207], v[102:105]
	v_mfma_f32_16x16x32_bf16 v[94:97], v[180:183], v[212:215], v[94:97]
	v_mfma_f32_16x16x32_bf16 v[86:89], v[188:191], v[212:215], v[86:89]
	v_mfma_f32_16x16x32_bf16 v[78:81], v[180:183], v[220:223], v[78:81]
	v_mfma_f32_16x16x32_bf16 v[70:73], v[188:191], v[220:223], v[70:73]
	s_setprio 0
	s_barrier
	s_add_i32 s74, s66, s54
	v_lshl_add_u64 v[148:149], s[50:51], 0, v[134:135]
	s_mov_b32 m0, s74
	ds_read_b128 v[192:195], v157 offset:16384
	ds_read_b128 v[196:199], v157 offset:17408
	ds_read_b128 v[200:203], v157 offset:18432
	ds_read_b128 v[204:207], v157 offset:19456
	ds_read_b128 v[208:211], v157 offset:20480
	ds_read_b128 v[212:215], v157 offset:21504
	ds_read_b128 v[216:219], v157 offset:22528
	ds_read_b128 v[220:223], v157 offset:23552
	global_load_lds_dwordx4 v[148:149], off
	s_add_i32 m0, s74, 0x2000
	s_add_u32 s74, s50, 0x40000
	v_lshl_add_u64 v[224:225], s[50:51], 0, v[130:131]
	s_addc_u32 s75, s51, 0
	s_add_i32 s76, s67, s54
	global_load_lds_dwordx4 v[224:225], off
	v_lshl_add_u64 v[226:227], s[74:75], 0, v[134:135]
	s_mov_b32 m0, s76
	v_lshl_add_u64 v[228:229], s[52:53], 0, v[132:133]
	global_load_lds_dwordx4 v[226:227], off
	v_lshl_add_u64 v[226:227], s[74:75], 0, v[130:131]
	s_add_i32 m0, s76, 0x2000
	s_nop 0
	global_load_lds_dwordx4 v[226:227], off
	v_lshl_add_u64 v[226:227], s[52:53], 0, v[136:137]
	s_mov_b32 m0, s57
	s_nop 0
	global_load_lds_dwordx4 v[226:227], off
	s_mov_b32 m0, s58
	s_nop 0
	global_load_lds_dwordx4 v[228:229], off
	s_waitcnt vmcnt(8)
	s_waitcnt lgkmcnt(0)
	s_setprio 1
	s_barrier
	v_mfma_f32_16x16x32_bf16 v[58:61], v[160:163], v[192:195], 0
	v_mfma_f32_16x16x32_bf16 v[50:53], v[168:171], v[192:195], 0
	v_mfma_f32_16x16x32_bf16 v[42:45], v[160:163], v[200:203], 0
	v_mfma_f32_16x16x32_bf16 v[34:37], v[168:171], v[200:203], 0
	v_mfma_f32_16x16x32_bf16 v[26:29], v[160:163], v[208:211], 0
	v_mfma_f32_16x16x32_bf16 v[18:21], v[168:171], v[208:211], 0
	v_mfma_f32_16x16x32_bf16 v[10:13], v[160:163], v[216:219], 0
	v_mfma_f32_16x16x32_bf16 v[6:9], v[168:171], v[216:219], 0
	v_mfma_f32_16x16x32_bf16 v[58:61], v[164:167], v[196:199], v[58:61]
	v_mfma_f32_16x16x32_bf16 v[50:53], v[172:175], v[196:199], v[50:53]
	v_mfma_f32_16x16x32_bf16 v[42:45], v[164:167], v[204:207], v[42:45]
	v_mfma_f32_16x16x32_bf16 v[34:37], v[172:175], v[204:207], v[34:37]
	v_mfma_f32_16x16x32_bf16 v[26:29], v[164:167], v[212:215], v[26:29]
	v_mfma_f32_16x16x32_bf16 v[18:21], v[172:175], v[212:215], v[18:21]
	v_mfma_f32_16x16x32_bf16 v[10:13], v[164:167], v[220:223], v[10:13]
	v_mfma_f32_16x16x32_bf16 v[6:9], v[172:175], v[220:223], v[6:9]
	s_setprio 0
	s_setprio 1
	v_mfma_f32_16x16x32_bf16 v[62:65], v[176:179], v[192:195], 0
	v_mfma_f32_16x16x32_bf16 v[54:57], v[184:187], v[192:195], 0
	v_mfma_f32_16x16x32_bf16 v[46:49], v[176:179], v[200:203], 0
	v_mfma_f32_16x16x32_bf16 v[38:41], v[184:187], v[200:203], 0
	v_mfma_f32_16x16x32_bf16 v[30:33], v[176:179], v[208:211], 0
	v_mfma_f32_16x16x32_bf16 v[22:25], v[184:187], v[208:211], 0
	v_mfma_f32_16x16x32_bf16 v[14:17], v[176:179], v[216:219], 0
	v_mfma_f32_16x16x32_bf16 v[2:5], v[184:187], v[216:219], 0
	v_mfma_f32_16x16x32_bf16 v[62:65], v[180:183], v[196:199], v[62:65]
	v_mfma_f32_16x16x32_bf16 v[54:57], v[188:191], v[196:199], v[54:57]
	v_mfma_f32_16x16x32_bf16 v[46:49], v[180:183], v[204:207], v[46:49]
	v_mfma_f32_16x16x32_bf16 v[38:41], v[188:191], v[204:207], v[38:41]
	v_mfma_f32_16x16x32_bf16 v[30:33], v[180:183], v[212:215], v[30:33]
	v_mfma_f32_16x16x32_bf16 v[22:25], v[188:191], v[212:215], v[22:25]
	v_mfma_f32_16x16x32_bf16 v[14:17], v[180:183], v[220:223], v[14:17]
	v_mfma_f32_16x16x32_bf16 v[2:5], v[188:191], v[220:223], v[2:5]
	s_setprio 0
	s_barrier
	s_add_i32 s74, 0, 0x18000
	v_add_u32_e32 v159, s74, v151
	s_add_i32 s75, 0, 0x1c000
	ds_read_b128 v[160:163], v159
	ds_read_b128 v[164:167], v159 offset:1024
	ds_read_b128 v[168:171], v159 offset:2048
	ds_read_b128 v[172:175], v159 offset:3072
	v_add_u32_e32 v159, s75, v151
	ds_read_b128 v[176:179], v159
	ds_read_b128 v[180:183], v159 offset:1024
	ds_read_b128 v[184:187], v159 offset:2048
	ds_read_b128 v[188:191], v159 offset:3072
	s_add_u32 s52, s52, 0x40000
	s_addc_u32 s53, s53, 0
	s_mov_b32 m0, s59
	v_lshl_add_u64 v[230:231], s[52:53], 0, v[136:137]
	ds_read_b128 v[192:195], v157 offset:32768
	ds_read_b128 v[196:199], v157 offset:33792
	ds_read_b128 v[200:203], v157 offset:34816
	ds_read_b128 v[204:207], v157 offset:35840
	ds_read_b128 v[208:211], v157 offset:36864
	ds_read_b128 v[212:215], v157 offset:37888
	ds_read_b128 v[216:219], v157 offset:38912
	ds_read_b128 v[220:223], v157 offset:39936
	global_load_lds_dwordx4 v[230:231], off
	v_lshl_add_u64 v[230:231], s[52:53], 0, v[132:133]
	s_mov_b32 m0, s60
	s_nop 0
	global_load_lds_dwordx4 v[230:231], off
	s_waitcnt vmcnt(8)
	s_waitcnt lgkmcnt(0)
	s_setprio 1
	s_barrier
	v_mfma_f32_16x16x32_bf16 v[118:121], v[160:163], v[192:195], v[118:121]
	v_mfma_f32_16x16x32_bf16 v[114:117], v[168:171], v[192:195], v[114:117]
	v_mfma_f32_16x16x32_bf16 v[106:109], v[160:163], v[200:203], v[106:109]
	v_mfma_f32_16x16x32_bf16 v[98:101], v[168:171], v[200:203], v[98:101]
	v_mfma_f32_16x16x32_bf16 v[90:93], v[160:163], v[208:211], v[90:93]
	v_mfma_f32_16x16x32_bf16 v[82:85], v[168:171], v[208:211], v[82:85]
	v_mfma_f32_16x16x32_bf16 v[74:77], v[160:163], v[216:219], v[74:77]
	v_mfma_f32_16x16x32_bf16 v[66:69], v[168:171], v[216:219], v[66:69]
	v_mfma_f32_16x16x32_bf16 v[118:121], v[164:167], v[196:199], v[118:121]
	v_mfma_f32_16x16x32_bf16 v[114:117], v[172:175], v[196:199], v[114:117]
	v_mfma_f32_16x16x32_bf16 v[106:109], v[164:167], v[204:207], v[106:109]
	v_mfma_f32_16x16x32_bf16 v[98:101], v[172:175], v[204:207], v[98:101]
	v_mfma_f32_16x16x32_bf16 v[90:93], v[164:167], v[212:215], v[90:93]
	v_mfma_f32_16x16x32_bf16 v[82:85], v[172:175], v[212:215], v[82:85]
	v_mfma_f32_16x16x32_bf16 v[74:77], v[164:167], v[220:223], v[74:77]
	v_mfma_f32_16x16x32_bf16 v[66:69], v[172:175], v[220:223], v[66:69]
	s_setprio 0
	s_setprio 1
	v_mfma_f32_16x16x32_bf16 v[126:129], v[176:179], v[192:195], v[126:129]
	v_mfma_f32_16x16x32_bf16 v[122:125], v[184:187], v[192:195], v[122:125]
	v_mfma_f32_16x16x32_bf16 v[110:113], v[176:179], v[200:203], v[110:113]
	v_mfma_f32_16x16x32_bf16 v[102:105], v[184:187], v[200:203], v[102:105]
	v_mfma_f32_16x16x32_bf16 v[94:97], v[176:179], v[208:211], v[94:97]
	v_mfma_f32_16x16x32_bf16 v[86:89], v[184:187], v[208:211], v[86:89]
	v_mfma_f32_16x16x32_bf16 v[78:81], v[176:179], v[216:219], v[78:81]
	v_mfma_f32_16x16x32_bf16 v[70:73], v[184:187], v[216:219], v[70:73]
	v_mfma_f32_16x16x32_bf16 v[126:129], v[180:183], v[196:199], v[126:129]
	v_mfma_f32_16x16x32_bf16 v[122:125], v[188:191], v[196:199], v[122:125]
	v_mfma_f32_16x16x32_bf16 v[110:113], v[180:183], v[204:207], v[110:113]
	v_mfma_f32_16x16x32_bf16 v[102:105], v[188:191], v[204:207], v[102:105]
	v_mfma_f32_16x16x32_bf16 v[94:97], v[180:183], v[212:215], v[94:97]
	v_mfma_f32_16x16x32_bf16 v[86:89], v[188:191], v[212:215], v[86:89]
	v_mfma_f32_16x16x32_bf16 v[78:81], v[180:183], v[220:223], v[78:81]
	v_mfma_f32_16x16x32_bf16 v[70:73], v[188:191], v[220:223], v[70:73]
	s_setprio 0
	s_barrier
	s_add_i32 s52, s74, s54
	v_lshl_add_u64 v[148:149], v[148:149], 0, s[14:15]
	s_mov_b32 m0, s52
	ds_read_b128 v[192:195], v157 offset:49152
	ds_read_b128 v[196:199], v157 offset:50176
	ds_read_b128 v[200:203], v157 offset:51200
	ds_read_b128 v[204:207], v157 offset:52224
	ds_read_b128 v[208:211], v157 offset:53248
	ds_read_b128 v[212:215], v157 offset:54272
	ds_read_b128 v[216:219], v157 offset:55296
	ds_read_b128 v[220:223], v157 offset:56320
	global_load_lds_dwordx4 v[148:149], off
	s_add_i32 m0, s52, 0x2000
	s_add_u32 s50, s50, 0x40080
	v_lshl_add_u64 v[148:149], v[224:225], 0, s[14:15]
	s_addc_u32 s51, s51, 0
	s_add_i32 s52, s75, s54
	global_load_lds_dwordx4 v[148:149], off
	v_lshl_add_u64 v[148:149], s[50:51], 0, v[134:135]
	s_mov_b32 m0, s52
	s_nop 0
	global_load_lds_dwordx4 v[148:149], off
	v_lshl_add_u64 v[148:149], s[50:51], 0, v[130:131]
	s_add_i32 m0, s52, 0x2000
	s_nop 0
	global_load_lds_dwordx4 v[148:149], off
	v_lshl_add_u64 v[148:149], v[226:227], 0, s[14:15]
	s_mov_b32 m0, s62
	s_nop 0
	global_load_lds_dwordx4 v[148:149], off
	v_lshl_add_u64 v[148:149], v[228:229], 0, s[14:15]
	s_mov_b32 m0, s63
	s_nop 0
	global_load_lds_dwordx4 v[148:149], off
	s_waitcnt vmcnt(8)
	s_waitcnt lgkmcnt(0)
	s_setprio 1
	s_barrier
	v_mfma_f32_16x16x32_bf16 v[58:61], v[160:163], v[192:195], v[58:61]
	v_mfma_f32_16x16x32_bf16 v[50:53], v[168:171], v[192:195], v[50:53]
	v_mfma_f32_16x16x32_bf16 v[42:45], v[160:163], v[200:203], v[42:45]
	v_mfma_f32_16x16x32_bf16 v[34:37], v[168:171], v[200:203], v[34:37]
	v_mfma_f32_16x16x32_bf16 v[26:29], v[160:163], v[208:211], v[26:29]
	v_mfma_f32_16x16x32_bf16 v[18:21], v[168:171], v[208:211], v[18:21]
	v_mfma_f32_16x16x32_bf16 v[10:13], v[160:163], v[216:219], v[10:13]
	v_mfma_f32_16x16x32_bf16 v[6:9], v[168:171], v[216:219], v[6:9]
	v_mfma_f32_16x16x32_bf16 v[58:61], v[164:167], v[196:199], v[58:61]
	v_mfma_f32_16x16x32_bf16 v[50:53], v[172:175], v[196:199], v[50:53]
	v_mfma_f32_16x16x32_bf16 v[42:45], v[164:167], v[204:207], v[42:45]
	v_mfma_f32_16x16x32_bf16 v[34:37], v[172:175], v[204:207], v[34:37]
	v_mfma_f32_16x16x32_bf16 v[26:29], v[164:167], v[212:215], v[26:29]
	v_mfma_f32_16x16x32_bf16 v[18:21], v[172:175], v[212:215], v[18:21]
	v_mfma_f32_16x16x32_bf16 v[10:13], v[164:167], v[220:223], v[10:13]
	v_mfma_f32_16x16x32_bf16 v[6:9], v[172:175], v[220:223], v[6:9]
	s_setprio 0
	s_setprio 1
	v_mfma_f32_16x16x32_bf16 v[62:65], v[176:179], v[192:195], v[62:65]
	v_mfma_f32_16x16x32_bf16 v[54:57], v[184:187], v[192:195], v[54:57]
	v_mfma_f32_16x16x32_bf16 v[46:49], v[176:179], v[200:203], v[46:49]
	v_mfma_f32_16x16x32_bf16 v[38:41], v[184:187], v[200:203], v[38:41]
	v_mfma_f32_16x16x32_bf16 v[30:33], v[176:179], v[208:211], v[30:33]
	v_mfma_f32_16x16x32_bf16 v[22:25], v[184:187], v[208:211], v[22:25]
	v_mfma_f32_16x16x32_bf16 v[14:17], v[176:179], v[216:219], v[14:17]
	v_mfma_f32_16x16x32_bf16 v[2:5], v[184:187], v[216:219], v[2:5]
	v_mfma_f32_16x16x32_bf16 v[62:65], v[180:183], v[196:199], v[62:65]
	v_mfma_f32_16x16x32_bf16 v[54:57], v[188:191], v[196:199], v[54:57]
	v_mfma_f32_16x16x32_bf16 v[46:49], v[180:183], v[204:207], v[46:49]
	v_mfma_f32_16x16x32_bf16 v[38:41], v[188:191], v[204:207], v[38:41]
	v_mfma_f32_16x16x32_bf16 v[30:33], v[180:183], v[212:215], v[30:33]
	v_mfma_f32_16x16x32_bf16 v[22:25], v[188:191], v[212:215], v[22:25]
	v_mfma_f32_16x16x32_bf16 v[14:17], v[180:183], v[220:223], v[14:17]
	v_mfma_f32_16x16x32_bf16 v[2:5], v[188:191], v[220:223], v[2:5]
	s_setprio 0
	s_barrier
	s_add_i32 s73, s73, 2
	s_add_u32 s48, s48, 0x100
	s_addc_u32 s49, s49, 0
	s_add_u32 s71, s71, 0x100
	s_addc_u32 s72, s72, 0
	s_cmp_gt_u32 s73, 13
	s_cbranch_scc0 .LBB0_152
	s_branch .Lz_post_p1

.Lz_post_p1:
	s_lshl_b32 s25, s46, 8
	v_add_u32_e32 v148, s25, v150
	v_ashrrev_i32_e32 v149, 31, v148
	v_lshl_add_u64 v[244:245], v[148:149], 2, s[8:9]
	global_load_dword v149, v[244:245], off
	global_load_dword v232, v[244:245], off offset:64
	global_load_dword v233, v[244:245], off offset:128
	global_load_dword v234, v[244:245], off offset:192
	global_load_dword v235, v[244:245], off offset:512
	global_load_dword v236, v[244:245], off offset:576
	global_load_dword v237, v[244:245], off offset:640
	global_load_dword v238, v[244:245], off offset:704
	v_pk_mul_f32 v[128:129], v[120:121], v[128:129]
	v_pk_mul_f32 v[126:127], v[118:119], v[126:127]
	v_pk_mul_f32 v[124:125], v[116:117], v[124:125]
	v_pk_mul_f32 v[244:245], v[114:115], v[122:123]
	v_add_u32_e32 v246, s25, v152
	s_lshl_b32 s46, s47, 7
	v_mov_b64_e32 v[122:123], s[12:13]
	s_ashr_i32 s47, s46, 31
	v_mad_i64_i32 v[248:249], s[48:49], v148, s68, v[122:123]
	s_lshl_b64 s[46:47], s[46:47], 1
	v_lshl_add_u64 v[248:249], v[248:249], 0, s[46:47]
	v_lshl_add_u64 v[248:249], v[248:249], 0, v[138:139]
	v_pk_mul_f32 v[112:113], v[108:109], v[112:113]
	v_pk_mul_f32 v[110:111], v[106:107], v[110:111]
	v_pk_mul_f32 v[104:105], v[100:101], v[104:105]
	v_pk_mul_f32 v[102:103], v[98:99], v[102:103]
	v_pk_mul_f32 v[96:97], v[92:93], v[96:97]
	v_pk_mul_f32 v[94:95], v[90:91], v[94:95]
	v_pk_mul_f32 v[88:89], v[84:85], v[88:89]
	v_pk_mul_f32 v[86:87], v[82:83], v[86:87]
	v_pk_mul_f32 v[80:81], v[76:77], v[80:81]
	v_pk_mul_f32 v[78:79], v[74:75], v[78:79]
	v_pk_mul_f32 v[72:73], v[68:69], v[72:73]
	v_pk_mul_f32 v[70:71], v[66:67], v[70:71]
	v_pk_mul_f32 v[64:65], v[60:61], v[64:65]
	v_pk_mul_f32 v[62:63], v[58:59], v[62:63]
	v_pk_mul_f32 v[56:57], v[52:53], v[56:57]
	v_pk_mul_f32 v[54:55], v[50:51], v[54:55]
	v_pk_mul_f32 v[48:49], v[44:45], v[48:49]
	v_pk_mul_f32 v[46:47], v[42:43], v[46:47]
	v_pk_mul_f32 v[40:41], v[36:37], v[40:41]
	v_pk_mul_f32 v[38:39], v[34:35], v[38:39]
	v_pk_mul_f32 v[32:33], v[28:29], v[32:33]
	v_pk_mul_f32 v[30:31], v[26:27], v[30:31]
	v_pk_mul_f32 v[24:25], v[20:21], v[24:25]
	v_pk_mul_f32 v[22:23], v[18:19], v[22:23]
	v_pk_mul_f32 v[16:17], v[12:13], v[16:17]
	v_pk_mul_f32 v[14:15], v[10:11], v[14:15]
	v_pk_mul_f32 v[4:5], v[8:9], v[4:5]
	v_pk_mul_f32 v[2:3], v[6:7], v[2:3]
	s_and_b64 vcc, exec, s[16:17]
	s_cbranch_vccz .LBB0_155
	s_barrier
.LBB0_155:
	ds_read_b128 v[160:163], v155
	ds_read_b128 v[164:167], v155 offset:1024
	ds_read_b128 v[168:171], v155 offset:2048
	ds_read_b128 v[172:175], v155 offset:3072
	ds_read_b128 v[176:179], v156
	ds_read_b128 v[180:183], v156 offset:1024
	ds_read_b128 v[184:187], v156 offset:2048
	ds_read_b128 v[188:191], v156 offset:3072
	ds_read_b128 v[192:195], v157
	ds_read_b128 v[196:199], v157 offset:1024
	ds_read_b128 v[200:203], v157 offset:2048
	ds_read_b128 v[204:207], v157 offset:3072
	ds_read_b128 v[208:211], v157 offset:4096
	ds_read_b128 v[212:215], v157 offset:5120
	ds_read_b128 v[216:219], v157 offset:6144
	ds_read_b128 v[220:223], v157 offset:7168
	s_andn2_b64 vcc, exec, s[4:5]
	s_waitcnt vmcnt(0)
	v_fmamk_f32 v239, v149, 0x3a800000, v158
	v_rsq_f32_e32 v149, v239
	s_nop 0
	v_mul_f32_e32 v252, 0xbfb8aa3b, v149
	v_pk_mul_f32 v[120:121], v[120:121], v[252:253] op_sel_hi:[1,0]
	v_pk_mul_f32 v[118:119], v[118:119], v[252:253] op_sel_hi:[1,0]
	v_pk_mul_f32 v[116:117], v[116:117], v[252:253] op_sel_hi:[1,0]
	v_pk_mul_f32 v[114:115], v[114:115], v[252:253] op_sel_hi:[1,0]
	v_exp_f32_e32 v118, v118
	v_exp_f32_e32 v119, v119
	v_exp_f32_e32 v120, v120
	v_exp_f32_e32 v121, v121
	v_exp_f32_e32 v114, v114
	v_exp_f32_e32 v115, v115
	v_exp_f32_e32 v116, v116
	v_exp_f32_e32 v117, v117
	v_fma_f32 v118, v118, v239, v239
	v_fma_f32 v119, v119, v239, v239
	v_fma_f32 v120, v120, v239, v239
	v_fma_f32 v121, v121, v239, v239
	v_fma_f32 v149, v114, v239, v239
	v_fma_f32 v159, v115, v239, v239
	v_fma_f32 v247, v116, v239, v239
	v_fma_f32 v252, v117, v239, v239
	v_rcp_f32_e32 v114, v118
	v_rcp_f32_e32 v115, v119
	v_rcp_f32_e32 v116, v120
	v_rcp_f32_e32 v117, v121
	v_rcp_f32_e32 v118, v149
	v_rcp_f32_e32 v119, v159
	v_rcp_f32_e32 v120, v247
	v_rcp_f32_e32 v121, v252
	v_pk_mul_f32 v[116:117], v[128:129], v[116:117]
	v_pk_mul_f32 v[114:115], v[126:127], v[114:115]
	v_pk_mul_f32 v[120:121], v[124:125], v[120:121]
	v_pk_mul_f32 v[118:119], v[244:245], v[118:119]
	v_cvt_pk_bf16_f32 v114, v114, v115
	v_cvt_pk_bf16_f32 v115, v116, v117
	v_cvt_pk_bf16_f32 v116, v118, v119
	v_cvt_pk_bf16_f32 v117, v120, v121
	global_store_dwordx4 v[248:249], v[114:117], off
	v_fmamk_f32 v239, v232, 0x3a800000, v158
	v_rsq_f32_e32 v121, v239
	v_add_u32_e32 v114, s25, v153
	v_mul_f32_e32 v120, 0xbfb8aa3b, v121
	v_pk_mul_f32 v[108:109], v[108:109], v[120:121] op_sel_hi:[1,0]
	v_pk_mul_f32 v[106:107], v[106:107], v[120:121] op_sel_hi:[1,0]
	v_pk_mul_f32 v[100:101], v[100:101], v[120:121] op_sel_hi:[1,0]
	v_pk_mul_f32 v[98:99], v[98:99], v[120:121] op_sel_hi:[1,0]
	v_exp_f32_e32 v106, v106
	v_exp_f32_e32 v107, v107
	v_exp_f32_e32 v108, v108
	v_exp_f32_e32 v109, v109
	v_exp_f32_e32 v98, v98
	v_exp_f32_e32 v99, v99
	v_exp_f32_e32 v100, v100
	v_exp_f32_e32 v101, v101
	v_fma_f32 v106, v106, v239, v239
	v_fma_f32 v107, v107, v239, v239
	v_fma_f32 v108, v108, v239, v239
	v_fma_f32 v109, v109, v239, v239
	v_fma_f32 v115, v98, v239, v239
	v_fma_f32 v120, v99, v239, v239
	v_fma_f32 v121, v100, v239, v239
	v_fma_f32 v125, v101, v239, v239
	v_rcp_f32_e32 v98, v106
	v_rcp_f32_e32 v99, v107
	v_rcp_f32_e32 v100, v108
	v_rcp_f32_e32 v101, v109
	v_rcp_f32_e32 v106, v115
	v_rcp_f32_e32 v107, v120
	v_rcp_f32_e32 v108, v121
	v_rcp_f32_e32 v109, v125
	v_mad_i64_i32 v[116:117], s[48:49], v246, s68, v[122:123]
	v_lshl_add_u64 v[116:117], v[116:117], 0, s[46:47]
	v_pk_mul_f32 v[100:101], v[112:113], v[100:101]
	v_pk_mul_f32 v[98:99], v[110:111], v[98:99]
	v_pk_mul_f32 v[104:105], v[104:105], v[108:109]
	v_pk_mul_f32 v[102:103], v[102:103], v[106:107]
	v_lshl_add_u64 v[116:117], v[116:117], 0, v[138:139]
	v_cvt_pk_bf16_f32 v98, v98, v99
	v_cvt_pk_bf16_f32 v99, v100, v101
	v_cvt_pk_bf16_f32 v100, v102, v103
	v_cvt_pk_bf16_f32 v101, v104, v105
	global_store_dwordx4 v[116:117], v[98:101], off
	v_fmamk_f32 v239, v233, 0x3a800000, v158
	v_rsq_f32_e32 v105, v239
	v_add_u32_e32 v98, s25, v154
	v_mul_f32_e32 v104, 0xbfb8aa3b, v105
	v_pk_mul_f32 v[92:93], v[92:93], v[104:105] op_sel_hi:[1,0]
	v_pk_mul_f32 v[90:91], v[90:91], v[104:105] op_sel_hi:[1,0]
	v_pk_mul_f32 v[84:85], v[84:85], v[104:105] op_sel_hi:[1,0]
	v_pk_mul_f32 v[82:83], v[82:83], v[104:105] op_sel_hi:[1,0]
	v_exp_f32_e32 v90, v90
	v_exp_f32_e32 v91, v91
	v_exp_f32_e32 v92, v92
	v_exp_f32_e32 v93, v93
	v_exp_f32_e32 v82, v82
	v_exp_f32_e32 v83, v83
	v_exp_f32_e32 v84, v84
	v_exp_f32_e32 v85, v85
	v_fma_f32 v90, v90, v239, v239
	v_fma_f32 v91, v91, v239, v239
	v_fma_f32 v92, v92, v239, v239
	v_fma_f32 v93, v93, v239, v239
	v_fma_f32 v99, v82, v239, v239
	v_fma_f32 v104, v83, v239, v239
	v_fma_f32 v105, v84, v239, v239
	v_fma_f32 v107, v85, v239, v239
	v_rcp_f32_e32 v82, v90
	v_rcp_f32_e32 v83, v91
	v_rcp_f32_e32 v84, v92
	v_rcp_f32_e32 v85, v93
	v_rcp_f32_e32 v90, v99
	v_rcp_f32_e32 v91, v104
	v_rcp_f32_e32 v92, v105
	v_rcp_f32_e32 v93, v107
	v_mad_i64_i32 v[100:101], s[48:49], v114, s68, v[122:123]
	v_lshl_add_u64 v[100:101], v[100:101], 0, s[46:47]
	v_pk_mul_f32 v[84:85], v[96:97], v[84:85]
	v_pk_mul_f32 v[82:83], v[94:95], v[82:83]
	v_pk_mul_f32 v[88:89], v[88:89], v[92:93]
	v_pk_mul_f32 v[86:87], v[86:87], v[90:91]
	v_lshl_add_u64 v[100:101], v[100:101], 0, v[138:139]
	v_cvt_pk_bf16_f32 v82, v82, v83
	v_cvt_pk_bf16_f32 v83, v84, v85
	v_cvt_pk_bf16_f32 v84, v86, v87
	v_cvt_pk_bf16_f32 v85, v88, v89
	global_store_dwordx4 v[100:101], v[82:85], off
	s_nop 0
	s_nop 0
	v_add_u32_e32 v84, 0x80, v148
	v_mad_i64_i32 v[82:83], s[48:49], v98, s68, v[122:123]
	v_lshl_add_u64 v[82:83], v[82:83], 0, s[46:47]
	v_lshl_add_u64 v[82:83], v[82:83], 0, v[138:139]
	v_fmamk_f32 v239, v234, 0x3a800000, v158
	v_rsq_f32_e32 v89, v239
	s_nop 0
	v_mul_f32_e32 v88, 0xbfb8aa3b, v89
	v_pk_mul_f32 v[76:77], v[76:77], v[88:89] op_sel_hi:[1,0]
	v_pk_mul_f32 v[74:75], v[74:75], v[88:89] op_sel_hi:[1,0]
	v_pk_mul_f32 v[68:69], v[68:69], v[88:89] op_sel_hi:[1,0]
	v_pk_mul_f32 v[66:67], v[66:67], v[88:89] op_sel_hi:[1,0]
	v_exp_f32_e32 v74, v74
	v_exp_f32_e32 v75, v75
	v_exp_f32_e32 v76, v76
	v_exp_f32_e32 v77, v77
	v_exp_f32_e32 v66, v66
	v_exp_f32_e32 v67, v67
	v_exp_f32_e32 v68, v68
	v_exp_f32_e32 v69, v69
	v_fma_f32 v74, v74, v239, v239
	v_fma_f32 v75, v75, v239, v239
	v_fma_f32 v76, v76, v239, v239
	v_fma_f32 v77, v77, v239, v239
	v_fma_f32 v85, v66, v239, v239
	v_fma_f32 v88, v67, v239, v239
	v_fma_f32 v89, v68, v239, v239
	v_fma_f32 v91, v69, v239, v239
	v_rcp_f32_e32 v66, v74
	v_rcp_f32_e32 v67, v75
	v_rcp_f32_e32 v68, v76
	v_rcp_f32_e32 v69, v77
	v_rcp_f32_e32 v74, v85
	v_rcp_f32_e32 v75, v88
	v_rcp_f32_e32 v76, v89
	v_rcp_f32_e32 v77, v91
	v_pk_mul_f32 v[68:69], v[80:81], v[68:69]
	v_pk_mul_f32 v[66:67], v[78:79], v[66:67]
	v_pk_mul_f32 v[72:73], v[72:73], v[76:77]
	v_pk_mul_f32 v[70:71], v[70:71], v[74:75]
	v_cvt_pk_bf16_f32 v66, v66, v67
	v_cvt_pk_bf16_f32 v67, v68, v69
	v_cvt_pk_bf16_f32 v68, v70, v71
	v_cvt_pk_bf16_f32 v69, v72, v73
	global_store_dwordx4 v[82:83], v[66:69], off
	v_fmamk_f32 v239, v235, 0x3a800000, v158
	v_rsq_f32_e32 v73, v239
	v_add_u32_e32 v66, 0x90, v148
	v_mul_f32_e32 v72, 0xbfb8aa3b, v73
	v_pk_mul_f32 v[60:61], v[60:61], v[72:73] op_sel_hi:[1,0]
	v_pk_mul_f32 v[58:59], v[58:59], v[72:73] op_sel_hi:[1,0]
	v_pk_mul_f32 v[52:53], v[52:53], v[72:73] op_sel_hi:[1,0]
	v_pk_mul_f32 v[50:51], v[50:51], v[72:73] op_sel_hi:[1,0]
	v_exp_f32_e32 v58, v58
	v_exp_f32_e32 v59, v59
	v_exp_f32_e32 v60, v60
	v_exp_f32_e32 v61, v61
	v_exp_f32_e32 v50, v50
	v_exp_f32_e32 v51, v51
	v_exp_f32_e32 v52, v52
	v_exp_f32_e32 v53, v53
	v_fma_f32 v58, v58, v239, v239
	v_fma_f32 v59, v59, v239, v239
	v_fma_f32 v60, v60, v239, v239
	v_fma_f32 v61, v61, v239, v239
	v_fma_f32 v67, v50, v239, v239
	v_fma_f32 v72, v51, v239, v239
	v_fma_f32 v73, v52, v239, v239
	v_fma_f32 v75, v53, v239, v239
	v_rcp_f32_e32 v50, v58
	v_rcp_f32_e32 v51, v59
	v_rcp_f32_e32 v52, v60
	v_rcp_f32_e32 v53, v61
	v_rcp_f32_e32 v58, v67
	v_rcp_f32_e32 v59, v72
	v_rcp_f32_e32 v60, v73
	v_rcp_f32_e32 v61, v75
	v_mad_i64_i32 v[68:69], s[48:49], v84, s68, v[122:123]
	v_lshl_add_u64 v[68:69], v[68:69], 0, s[46:47]
	v_pk_mul_f32 v[52:53], v[64:65], v[52:53]
	v_pk_mul_f32 v[50:51], v[62:63], v[50:51]
	v_pk_mul_f32 v[56:57], v[56:57], v[60:61]
	v_pk_mul_f32 v[54:55], v[54:55], v[58:59]
	v_lshl_add_u64 v[68:69], v[68:69], 0, v[138:139]
	v_cvt_pk_bf16_f32 v50, v50, v51
	v_cvt_pk_bf16_f32 v51, v52, v53
	v_cvt_pk_bf16_f32 v52, v54, v55
	v_cvt_pk_bf16_f32 v53, v56, v57
	global_store_dwordx4 v[68:69], v[50:53], off
	v_fmamk_f32 v239, v236, 0x3a800000, v158
	v_rsq_f32_e32 v57, v239
	v_add_u32_e32 v50, 0xa0, v148
	v_mul_f32_e32 v56, 0xbfb8aa3b, v57
	v_pk_mul_f32 v[44:45], v[44:45], v[56:57] op_sel_hi:[1,0]
	v_pk_mul_f32 v[42:43], v[42:43], v[56:57] op_sel_hi:[1,0]
	v_pk_mul_f32 v[36:37], v[36:37], v[56:57] op_sel_hi:[1,0]
	v_pk_mul_f32 v[34:35], v[34:35], v[56:57] op_sel_hi:[1,0]
	v_exp_f32_e32 v42, v42
	v_exp_f32_e32 v43, v43
	v_exp_f32_e32 v44, v44
	v_exp_f32_e32 v45, v45
	v_exp_f32_e32 v34, v34
	v_exp_f32_e32 v35, v35
	v_exp_f32_e32 v36, v36
	v_exp_f32_e32 v37, v37
	v_fma_f32 v42, v42, v239, v239
	v_fma_f32 v43, v43, v239, v239
	v_fma_f32 v44, v44, v239, v239
	v_fma_f32 v45, v45, v239, v239
	v_fma_f32 v51, v34, v239, v239
	v_fma_f32 v56, v35, v239, v239
	v_fma_f32 v57, v36, v239, v239
	v_fma_f32 v59, v37, v239, v239
	v_rcp_f32_e32 v34, v42
	v_rcp_f32_e32 v35, v43
	v_rcp_f32_e32 v36, v44
	v_rcp_f32_e32 v37, v45
	v_rcp_f32_e32 v42, v51
	v_rcp_f32_e32 v43, v56
	v_rcp_f32_e32 v44, v57
	v_rcp_f32_e32 v45, v59
	v_mad_i64_i32 v[52:53], s[48:49], v66, s68, v[122:123]
	v_lshl_add_u64 v[52:53], v[52:53], 0, s[46:47]
	v_pk_mul_f32 v[36:37], v[48:49], v[36:37]
	v_pk_mul_f32 v[34:35], v[46:47], v[34:35]
	v_pk_mul_f32 v[40:41], v[40:41], v[44:45]
	v_pk_mul_f32 v[38:39], v[38:39], v[42:43]
	v_lshl_add_u64 v[52:53], v[52:53], 0, v[138:139]
	v_cvt_pk_bf16_f32 v34, v34, v35
	v_cvt_pk_bf16_f32 v35, v36, v37
	v_cvt_pk_bf16_f32 v36, v38, v39
	v_cvt_pk_bf16_f32 v37, v40, v41
	global_store_dwordx4 v[52:53], v[34:37], off
	v_fmamk_f32 v239, v237, 0x3a800000, v158
	v_rsq_f32_e32 v41, v239
	v_add_u32_e32 v34, 0xb0, v148
	v_mul_f32_e32 v40, 0xbfb8aa3b, v41
	v_pk_mul_f32 v[28:29], v[28:29], v[40:41] op_sel_hi:[1,0]
	v_pk_mul_f32 v[26:27], v[26:27], v[40:41] op_sel_hi:[1,0]
	v_pk_mul_f32 v[20:21], v[20:21], v[40:41] op_sel_hi:[1,0]
	v_pk_mul_f32 v[18:19], v[18:19], v[40:41] op_sel_hi:[1,0]
	v_exp_f32_e32 v26, v26
	v_exp_f32_e32 v27, v27
	v_exp_f32_e32 v28, v28
	v_exp_f32_e32 v29, v29
	v_exp_f32_e32 v18, v18
	v_exp_f32_e32 v19, v19
	v_exp_f32_e32 v20, v20
	v_exp_f32_e32 v21, v21
	v_fma_f32 v26, v26, v239, v239
	v_fma_f32 v27, v27, v239, v239
	v_fma_f32 v28, v28, v239, v239
	v_fma_f32 v29, v29, v239, v239
	v_fma_f32 v35, v18, v239, v239
	v_fma_f32 v40, v19, v239, v239
	v_fma_f32 v41, v20, v239, v239
	v_fma_f32 v43, v21, v239, v239
	v_rcp_f32_e32 v18, v26
	v_rcp_f32_e32 v19, v27
	v_rcp_f32_e32 v20, v28
	v_rcp_f32_e32 v21, v29
	v_rcp_f32_e32 v26, v35
	v_rcp_f32_e32 v27, v40
	v_rcp_f32_e32 v28, v41
	v_rcp_f32_e32 v29, v43
	v_mad_i64_i32 v[36:37], s[48:49], v50, s68, v[122:123]
	v_lshl_add_u64 v[36:37], v[36:37], 0, s[46:47]
	v_pk_mul_f32 v[20:21], v[32:33], v[20:21]
	v_pk_mul_f32 v[18:19], v[30:31], v[18:19]
	v_pk_mul_f32 v[24:25], v[24:25], v[28:29]
	v_pk_mul_f32 v[22:23], v[22:23], v[26:27]
	v_lshl_add_u64 v[36:37], v[36:37], 0, v[138:139]
	v_cvt_pk_bf16_f32 v18, v18, v19
	v_cvt_pk_bf16_f32 v19, v20, v21
	v_cvt_pk_bf16_f32 v20, v22, v23
	v_cvt_pk_bf16_f32 v21, v24, v25
	global_store_dwordx4 v[36:37], v[18:21], off
	s_nop 0
	s_nop 0
	v_fmamk_f32 v239, v238, 0x3a800000, v158
	v_rsq_f32_e32 v21, v239
	v_mad_i64_i32 v[18:19], s[4:5], v34, s68, v[122:123]
	v_lshl_add_u64 v[18:19], v[18:19], 0, s[46:47]
	v_mul_f32_e32 v20, 0xbfb8aa3b, v21
	v_pk_mul_f32 v[12:13], v[12:13], v[20:21] op_sel_hi:[1,0]
	v_pk_mul_f32 v[10:11], v[10:11], v[20:21] op_sel_hi:[1,0]
	v_pk_mul_f32 v[8:9], v[8:9], v[20:21] op_sel_hi:[1,0]
	v_pk_mul_f32 v[6:7], v[6:7], v[20:21] op_sel_hi:[1,0]
	v_exp_f32_e32 v10, v10
	v_exp_f32_e32 v11, v11
	v_exp_f32_e32 v12, v12
	v_exp_f32_e32 v13, v13
	v_exp_f32_e32 v6, v6
	v_exp_f32_e32 v7, v7
	v_exp_f32_e32 v8, v8
	v_exp_f32_e32 v9, v9
	v_fma_f32 v10, v10, v239, v239
	v_fma_f32 v11, v11, v239, v239
	v_fma_f32 v12, v12, v239, v239
	v_fma_f32 v13, v13, v239, v239
	v_fma_f32 v20, v6, v239, v239
	v_fma_f32 v21, v7, v239, v239
	v_fma_f32 v23, v8, v239, v239
	v_fma_f32 v24, v9, v239, v239
	v_rcp_f32_e32 v6, v10
	v_rcp_f32_e32 v7, v11
	v_rcp_f32_e32 v8, v12
	v_rcp_f32_e32 v9, v13
	v_rcp_f32_e32 v10, v20
	v_rcp_f32_e32 v11, v21
	v_rcp_f32_e32 v12, v23
	v_rcp_f32_e32 v13, v24
	v_pk_mul_f32 v[8:9], v[16:17], v[8:9]
	v_pk_mul_f32 v[6:7], v[14:15], v[6:7]
	v_pk_mul_f32 v[12:13], v[4:5], v[12:13]
	v_pk_mul_f32 v[4:5], v[2:3], v[10:11]
	v_lshl_add_u64 v[18:19], v[18:19], 0, v[138:139]
	v_cvt_pk_bf16_f32 v2, v6, v7
	v_cvt_pk_bf16_f32 v3, v8, v9
	v_cvt_pk_bf16_f32 v4, v4, v5
	v_cvt_pk_bf16_f32 v5, v12, v13
	s_mov_b64 s[4:5], -1
	global_store_dwordx4 v[18:19], v[2:5], off
	s_cbranch_vccnz .LBB0_148
	s_andn2_b64 vcc, exec, s[10:11]
	s_cbranch_vccnz .LBB0_147
	s_barrier
	s_branch .LBB0_147

.LBB0_834:
	s_waitcnt lgkmcnt(0)
	s_add_u32 s10, s10, 0x40000
	s_addc_u32 s11, s11, 0
	s_add_u32 s12, s4, 0xa400000
	s_addc_u32 s13, s5, 0
	s_lshl_b32 s4, s14, 5
	s_mov_b64 s[14:15], 0x80
	s_and_b32 s26, s4, 0x60
	s_add_i32 m0, s57, 0x18000
	v_lshl_add_u64 v[8:9], v[8:9], 0, s[14:15]
	s_lshl_b32 s25, s24, 13
	s_lshl_b32 s27, s26, 7
	s_waitcnt vmcnt(2)
	s_barrier
	global_load_lds_dwordx4 v[8:9], off
	v_lshl_add_u64 v[6:7], v[6:7], 0, s[14:15]
	s_add_i32 m0, s57, 0x1a000
	s_add_i32 s62, s57, 0x8000
	s_add_i32 s63, s57, 0xa000
	global_load_lds_dwordx4 v[6:7], off
	v_lshl_add_u64 v[2:3], v[2:3], 0, s[14:15]
	s_mov_b32 m0, s62
	s_add_u32 s4, s50, 0x40080
	global_load_lds_dwordx4 v[2:3], off
	v_lshl_add_u64 v[2:3], v[4:5], 0, s[14:15]
	s_mov_b32 m0, s63
	s_addc_u32 s5, s51, 0
	global_load_lds_dwordx4 v[2:3], off
	s_add_i32 m0, s57, 0x1c000
	v_lshl_add_u64 v[2:3], s[4:5], 0, v[134:135]
	global_load_lds_dwordx4 v[2:3], off
	v_lshl_add_u64 v[2:3], s[4:5], 0, v[130:131]
	s_add_i32 m0, s57, 0x1e000
	s_cmpk_lt_u32 s17, 0x100
	global_load_lds_dwordx4 v[2:3], off
	v_lshrrev_b32_e32 v3, 1, v10
	v_and_b32_e32 v3, 24, v3
	v_and_b32_e32 v2, 15, v10
	v_lshlrev_b32_e32 v4, 1, v3
	v_lshl_or_b32 v150, s24, 6, v2
	v_lshl_or_b32 v2, v2, 6, v4
	v_lshlrev_b32_e32 v4, 2, v10
	v_and_b32_e32 v4, 32, v4
	v_bitop3_b32 v5, v2, s25, v4 bitop3:0xde
	v_bitop3_b32 v151, v2, s27, v4 bitop3:0xde
	v_or_b32_e32 v2, s26, v3
	v_lshlrev_b32_e32 v3, 14, v15
	v_and_b32_e32 v3, 0xffff8000, v3
	v_lshl_add_u32 v3, v14, 11, v3
	v_and_b32_e32 v4, 1, v15
	v_lshl_or_b32 v3, v4, 6, v3
	v_lshl_add_u32 v140, v16, 1, v3
	v_lshlrev_b32_e32 v3, 14, v11
	v_and_b32_e32 v3, 0xffff8000, v3
	s_waitcnt vmcnt(6)
	v_lshl_add_u32 v3, v12, 11, v3
	v_and_b32_e32 v4, 1, v11
	s_sext_i32_i16 s47, s16
	s_cselect_b64 s[16:17], -1, 0
	v_lshl_or_b32 v3, v4, 6, v3
	s_add_i32 s66, 0, 0x10000
	s_add_i32 s67, 0, 0x14000
	v_or_b32_e32 v152, 16, v150
	v_or_b32_e32 v153, 32, v150
	v_or_b32_e32 v154, 48, v150
	s_ashr_i32 s64, s38, 31
	s_mov_b32 s65, s38
	v_mov_b32_e32 v141, v139
	v_lshl_add_u32 v142, v13, 1, v3
	v_mov_b32_e32 v143, v139
	v_mov_b64_e32 v[144:145], 0xb00
	v_mov_b64_e32 v[146:147], 0xaff
	v_add_u32_e32 v155, s66, v151
	v_add_u32_e32 v156, s67, v151
	v_add_u32_e32 v157, 0, v5
	v_mov_b32_e32 v158, 0x358637bd
	s_movk_i32 s68, 0x1600
	v_lshlrev_b32_e32 v138, 1, v2
	s_barrier
	ds_read_b128 v[160:163], v155
	ds_read_b128 v[164:167], v155 offset:1024
	ds_read_b128 v[168:171], v155 offset:2048
	ds_read_b128 v[172:175], v155 offset:3072
	ds_read_b128 v[176:179], v156
	ds_read_b128 v[180:183], v156 offset:1024
	ds_read_b128 v[184:187], v156 offset:2048
	ds_read_b128 v[188:191], v156 offset:3072
	ds_read_b128 v[192:195], v157
	ds_read_b128 v[196:199], v157 offset:1024
	ds_read_b128 v[200:203], v157 offset:2048
	ds_read_b128 v[204:207], v157 offset:3072
	ds_read_b128 v[208:211], v157 offset:4096
	ds_read_b128 v[212:215], v157 offset:5120
	ds_read_b128 v[216:219], v157 offset:6144
	ds_read_b128 v[220:223], v157 offset:7168
	s_branch .LBB0_837

.LBB0_839:
	s_ashr_i32 s27, s26, 31
	s_lshl_b64 s[42:43], s[26:27], 19
	s_add_u32 s42, s3, s42
	s_addc_u32 s43, s23, s43
	s_and_b64 s[44:45], s[4:5], exec
	s_cselect_b32 s27, s43, s49
	s_cselect_b32 s69, s42, s48
	s_ashr_i32 s25, s24, 31
	s_lshl_b64 s[44:45], s[24:25], 19
	s_add_u32 s44, s29, s44
	s_addc_u32 s45, s31, s45
	s_and_b64 s[52:53], s[4:5], exec
	s_cselect_b32 s25, s45, s51
	s_cselect_b32 s70, s44, s50
	s_add_u32 s48, s48, 0x40080
	s_addc_u32 s49, s49, 0
	s_add_u32 s71, s50, 0x100
	s_addc_u32 s72, s51, 0
	s_mov_b32 s73, -2
	s_waitcnt vmcnt(0)
	s_add_u32 s50, s48, 0xfffc0080
	s_addc_u32 s51, s49, -1
	s_cmp_eq_u32 s73, 12
	s_cselect_b32 s53, s27, s51
	s_cselect_b32 s52, s69, s50
	s_cselect_b32 s51, s25, s72
	s_cselect_b32 s50, s70, s71
	v_lshl_add_u64 v[148:149], s[48:49], 0, v[140:141]
	s_add_i32 m0, s57, 0xc000
	global_load_lds_dwordx4 v[148:149], off
	v_lshl_add_u64 v[148:149], s[48:49], 0, v[142:143]
	s_add_i32 m0, s57, 0xe000
	s_nop 0
	global_load_lds_dwordx4 v[148:149], off
	s_waitcnt vmcnt(8)
	s_waitcnt lgkmcnt(0)
	s_setprio 1
	s_barrier
	v_mfma_f32_16x16x32_bf16 v[118:121], v[160:163], v[192:195], 0
	v_mfma_f32_16x16x32_bf16 v[114:117], v[168:171], v[192:195], 0
	v_mfma_f32_16x16x32_bf16 v[106:109], v[160:163], v[200:203], 0
	v_mfma_f32_16x16x32_bf16 v[98:101], v[168:171], v[200:203], 0
	v_mfma_f32_16x16x32_bf16 v[90:93], v[160:163], v[208:211], 0
	v_mfma_f32_16x16x32_bf16 v[82:85], v[168:171], v[208:211], 0
	v_mfma_f32_16x16x32_bf16 v[74:77], v[160:163], v[216:219], 0
	v_mfma_f32_16x16x32_bf16 v[66:69], v[168:171], v[216:219], 0
	v_mfma_f32_16x16x32_bf16 v[118:121], v[164:167], v[196:199], v[118:121]
	v_mfma_f32_16x16x32_bf16 v[114:117], v[172:175], v[196:199], v[114:117]
	v_mfma_f32_16x16x32_bf16 v[106:109], v[164:167], v[204:207], v[106:109]
	v_mfma_f32_16x16x32_bf16 v[98:101], v[172:175], v[204:207], v[98:101]
	v_mfma_f32_16x16x32_bf16 v[90:93], v[164:167], v[212:215], v[90:93]
	v_mfma_f32_16x16x32_bf16 v[82:85], v[172:175], v[212:215], v[82:85]
	v_mfma_f32_16x16x32_bf16 v[74:77], v[164:167], v[220:223], v[74:77]
	v_mfma_f32_16x16x32_bf16 v[66:69], v[172:175], v[220:223], v[66:69]
	s_setprio 0
	s_setprio 1
	v_mfma_f32_16x16x32_bf16 v[126:129], v[176:179], v[192:195], 0
	v_mfma_f32_16x16x32_bf16 v[122:125], v[184:187], v[192:195], 0
	v_mfma_f32_16x16x32_bf16 v[110:113], v[176:179], v[200:203], 0
	v_mfma_f32_16x16x32_bf16 v[102:105], v[184:187], v[200:203], 0
	v_mfma_f32_16x16x32_bf16 v[94:97], v[176:179], v[208:211], 0
	v_mfma_f32_16x16x32_bf16 v[86:89], v[184:187], v[208:211], 0
	v_mfma_f32_16x16x32_bf16 v[78:81], v[176:179], v[216:219], 0
	v_mfma_f32_16x16x32_bf16 v[70:73], v[184:187], v[216:219], 0
	v_mfma_f32_16x16x32_bf16 v[126:129], v[180:183], v[196:199], v[126:129]
	v_mfma_f32_16x16x32_bf16 v[122:125], v[188:191], v[196:199], v[122:125]
	v_mfma_f32_16x16x32_bf16 v[110:113], v[180:183], v[204:207], v[110:113]
	v_mfma_f32_16x16x32_bf16 v[102:105], v[188:191], v[204:207], v[102:105]
	v_mfma_f32_16x16x32_bf16 v[94:97], v[180:183], v[212:215], v[94:97]
	v_mfma_f32_16x16x32_bf16 v[86:89], v[188:191], v[212:215], v[86:89]
	v_mfma_f32_16x16x32_bf16 v[78:81], v[180:183], v[220:223], v[78:81]
	v_mfma_f32_16x16x32_bf16 v[70:73], v[188:191], v[220:223], v[70:73]
	s_setprio 0
	s_barrier
	s_add_i32 s74, s66, s54
	v_lshl_add_u64 v[148:149], s[50:51], 0, v[134:135]
	s_mov_b32 m0, s74
	ds_read_b128 v[192:195], v157 offset:16384
	ds_read_b128 v[196:199], v157 offset:17408
	ds_read_b128 v[200:203], v157 offset:18432
	ds_read_b128 v[204:207], v157 offset:19456
	ds_read_b128 v[208:211], v157 offset:20480
	ds_read_b128 v[212:215], v157 offset:21504
	ds_read_b128 v[216:219], v157 offset:22528
	ds_read_b128 v[220:223], v157 offset:23552
	global_load_lds_dwordx4 v[148:149], off
	s_add_i32 m0, s74, 0x2000
	s_add_u32 s74, s50, 0x40000
	v_lshl_add_u64 v[224:225], s[50:51], 0, v[130:131]
	s_addc_u32 s75, s51, 0
	s_add_i32 s76, s67, s54
	global_load_lds_dwordx4 v[224:225], off
	v_lshl_add_u64 v[226:227], s[74:75], 0, v[134:135]
	s_mov_b32 m0, s76
	v_lshl_add_u64 v[228:229], s[52:53], 0, v[132:133]
	global_load_lds_dwordx4 v[226:227], off
	v_lshl_add_u64 v[226:227], s[74:75], 0, v[130:131]
	s_add_i32 m0, s76, 0x2000
	s_nop 0
	global_load_lds_dwordx4 v[226:227], off
	v_lshl_add_u64 v[226:227], s[52:53], 0, v[136:137]
	s_mov_b32 m0, s57
	s_nop 0
	global_load_lds_dwordx4 v[226:227], off
	s_mov_b32 m0, s58
	s_nop 0
	global_load_lds_dwordx4 v[228:229], off
	s_waitcnt vmcnt(8)
	s_waitcnt lgkmcnt(0)
	s_setprio 1
	s_barrier
	v_mfma_f32_16x16x32_bf16 v[58:61], v[160:163], v[192:195], 0
	v_mfma_f32_16x16x32_bf16 v[50:53], v[168:171], v[192:195], 0
	v_mfma_f32_16x16x32_bf16 v[42:45], v[160:163], v[200:203], 0
	v_mfma_f32_16x16x32_bf16 v[34:37], v[168:171], v[200:203], 0
	v_mfma_f32_16x16x32_bf16 v[26:29], v[160:163], v[208:211], 0
	v_mfma_f32_16x16x32_bf16 v[18:21], v[168:171], v[208:211], 0
	v_mfma_f32_16x16x32_bf16 v[10:13], v[160:163], v[216:219], 0
	v_mfma_f32_16x16x32_bf16 v[6:9], v[168:171], v[216:219], 0
	v_mfma_f32_16x16x32_bf16 v[58:61], v[164:167], v[196:199], v[58:61]
	v_mfma_f32_16x16x32_bf16 v[50:53], v[172:175], v[196:199], v[50:53]
	v_mfma_f32_16x16x32_bf16 v[42:45], v[164:167], v[204:207], v[42:45]
	v_mfma_f32_16x16x32_bf16 v[34:37], v[172:175], v[204:207], v[34:37]
	v_mfma_f32_16x16x32_bf16 v[26:29], v[164:167], v[212:215], v[26:29]
	v_mfma_f32_16x16x32_bf16 v[18:21], v[172:175], v[212:215], v[18:21]
	v_mfma_f32_16x16x32_bf16 v[10:13], v[164:167], v[220:223], v[10:13]
	v_mfma_f32_16x16x32_bf16 v[6:9], v[172:175], v[220:223], v[6:9]
	s_setprio 0
	s_setprio 1
	v_mfma_f32_16x16x32_bf16 v[62:65], v[176:179], v[192:195], 0
	v_mfma_f32_16x16x32_bf16 v[54:57], v[184:187], v[192:195], 0
	v_mfma_f32_16x16x32_bf16 v[46:49], v[176:179], v[200:203], 0
	v_mfma_f32_16x16x32_bf16 v[38:41], v[184:187], v[200:203], 0
	v_mfma_f32_16x16x32_bf16 v[30:33], v[176:179], v[208:211], 0
	v_mfma_f32_16x16x32_bf16 v[22:25], v[184:187], v[208:211], 0
	v_mfma_f32_16x16x32_bf16 v[14:17], v[176:179], v[216:219], 0
	v_mfma_f32_16x16x32_bf16 v[2:5], v[184:187], v[216:219], 0
	v_mfma_f32_16x16x32_bf16 v[62:65], v[180:183], v[196:199], v[62:65]
	v_mfma_f32_16x16x32_bf16 v[54:57], v[188:191], v[196:199], v[54:57]
	v_mfma_f32_16x16x32_bf16 v[46:49], v[180:183], v[204:207], v[46:49]
	v_mfma_f32_16x16x32_bf16 v[38:41], v[188:191], v[204:207], v[38:41]
	v_mfma_f32_16x16x32_bf16 v[30:33], v[180:183], v[212:215], v[30:33]
	v_mfma_f32_16x16x32_bf16 v[22:25], v[188:191], v[212:215], v[22:25]
	v_mfma_f32_16x16x32_bf16 v[14:17], v[180:183], v[220:223], v[14:17]
	v_mfma_f32_16x16x32_bf16 v[2:5], v[188:191], v[220:223], v[2:5]
	s_setprio 0
	s_barrier
	s_add_i32 s74, 0, 0x18000
	v_add_u32_e32 v159, s74, v151
	s_add_i32 s75, 0, 0x1c000
	ds_read_b128 v[160:163], v159
	ds_read_b128 v[164:167], v159 offset:1024
	ds_read_b128 v[168:171], v159 offset:2048
	ds_read_b128 v[172:175], v159 offset:3072
	v_add_u32_e32 v159, s75, v151
	ds_read_b128 v[176:179], v159
	ds_read_b128 v[180:183], v159 offset:1024
	ds_read_b128 v[184:187], v159 offset:2048
	ds_read_b128 v[188:191], v159 offset:3072
	s_add_u32 s52, s52, 0x40000
	s_addc_u32 s53, s53, 0
	s_mov_b32 m0, s59
	v_lshl_add_u64 v[230:231], s[52:53], 0, v[136:137]
	ds_read_b128 v[192:195], v157 offset:32768
	ds_read_b128 v[196:199], v157 offset:33792
	ds_read_b128 v[200:203], v157 offset:34816
	ds_read_b128 v[204:207], v157 offset:35840
	ds_read_b128 v[208:211], v157 offset:36864
	ds_read_b128 v[212:215], v157 offset:37888
	ds_read_b128 v[216:219], v157 offset:38912
	ds_read_b128 v[220:223], v157 offset:39936
	global_load_lds_dwordx4 v[230:231], off
	v_lshl_add_u64 v[230:231], s[52:53], 0, v[132:133]
	s_mov_b32 m0, s60
	s_nop 0
	global_load_lds_dwordx4 v[230:231], off
	s_waitcnt vmcnt(8)
	s_waitcnt lgkmcnt(0)
	s_setprio 1
	s_barrier
	v_mfma_f32_16x16x32_bf16 v[118:121], v[160:163], v[192:195], v[118:121]
	v_mfma_f32_16x16x32_bf16 v[114:117], v[168:171], v[192:195], v[114:117]
	v_mfma_f32_16x16x32_bf16 v[106:109], v[160:163], v[200:203], v[106:109]
	v_mfma_f32_16x16x32_bf16 v[98:101], v[168:171], v[200:203], v[98:101]
	v_mfma_f32_16x16x32_bf16 v[90:93], v[160:163], v[208:211], v[90:93]
	v_mfma_f32_16x16x32_bf16 v[82:85], v[168:171], v[208:211], v[82:85]
	v_mfma_f32_16x16x32_bf16 v[74:77], v[160:163], v[216:219], v[74:77]
	v_mfma_f32_16x16x32_bf16 v[66:69], v[168:171], v[216:219], v[66:69]
	v_mfma_f32_16x16x32_bf16 v[118:121], v[164:167], v[196:199], v[118:121]
	v_mfma_f32_16x16x32_bf16 v[114:117], v[172:175], v[196:199], v[114:117]
	v_mfma_f32_16x16x32_bf16 v[106:109], v[164:167], v[204:207], v[106:109]
	v_mfma_f32_16x16x32_bf16 v[98:101], v[172:175], v[204:207], v[98:101]
	v_mfma_f32_16x16x32_bf16 v[90:93], v[164:167], v[212:215], v[90:93]
	v_mfma_f32_16x16x32_bf16 v[82:85], v[172:175], v[212:215], v[82:85]
	v_mfma_f32_16x16x32_bf16 v[74:77], v[164:167], v[220:223], v[74:77]
	v_mfma_f32_16x16x32_bf16 v[66:69], v[172:175], v[220:223], v[66:69]
	s_setprio 0
	s_setprio 1
	v_mfma_f32_16x16x32_bf16 v[126:129], v[176:179], v[192:195], v[126:129]
	v_mfma_f32_16x16x32_bf16 v[122:125], v[184:187], v[192:195], v[122:125]
	v_mfma_f32_16x16x32_bf16 v[110:113], v[176:179], v[200:203], v[110:113]
	v_mfma_f32_16x16x32_bf16 v[102:105], v[184:187], v[200:203], v[102:105]
	v_mfma_f32_16x16x32_bf16 v[94:97], v[176:179], v[208:211], v[94:97]
	v_mfma_f32_16x16x32_bf16 v[86:89], v[184:187], v[208:211], v[86:89]
	v_mfma_f32_16x16x32_bf16 v[78:81], v[176:179], v[216:219], v[78:81]
	v_mfma_f32_16x16x32_bf16 v[70:73], v[184:187], v[216:219], v[70:73]
	v_mfma_f32_16x16x32_bf16 v[126:129], v[180:183], v[196:199], v[126:129]
	v_mfma_f32_16x16x32_bf16 v[122:125], v[188:191], v[196:199], v[122:125]
	v_mfma_f32_16x16x32_bf16 v[110:113], v[180:183], v[204:207], v[110:113]
	v_mfma_f32_16x16x32_bf16 v[102:105], v[188:191], v[204:207], v[102:105]
	v_mfma_f32_16x16x32_bf16 v[94:97], v[180:183], v[212:215], v[94:97]
	v_mfma_f32_16x16x32_bf16 v[86:89], v[188:191], v[212:215], v[86:89]
	v_mfma_f32_16x16x32_bf16 v[78:81], v[180:183], v[220:223], v[78:81]
	v_mfma_f32_16x16x32_bf16 v[70:73], v[188:191], v[220:223], v[70:73]
	s_setprio 0
	s_barrier
	s_add_i32 s52, s74, s54
	v_lshl_add_u64 v[148:149], v[148:149], 0, s[14:15]
	s_mov_b32 m0, s52
	ds_read_b128 v[192:195], v157 offset:49152
	ds_read_b128 v[196:199], v157 offset:50176
	ds_read_b128 v[200:203], v157 offset:51200
	ds_read_b128 v[204:207], v157 offset:52224
	ds_read_b128 v[208:211], v157 offset:53248
	ds_read_b128 v[212:215], v157 offset:54272
	ds_read_b128 v[216:219], v157 offset:55296
	ds_read_b128 v[220:223], v157 offset:56320
	global_load_lds_dwordx4 v[148:149], off
	s_add_i32 m0, s52, 0x2000
	s_add_u32 s50, s50, 0x40080
	v_lshl_add_u64 v[148:149], v[224:225], 0, s[14:15]
	s_addc_u32 s51, s51, 0
	s_add_i32 s52, s75, s54
	global_load_lds_dwordx4 v[148:149], off
	v_lshl_add_u64 v[148:149], s[50:51], 0, v[134:135]
	s_mov_b32 m0, s52
	s_nop 0
	global_load_lds_dwordx4 v[148:149], off
	v_lshl_add_u64 v[148:149], s[50:51], 0, v[130:131]
	s_add_i32 m0, s52, 0x2000
	s_nop 0
	global_load_lds_dwordx4 v[148:149], off
	v_lshl_add_u64 v[148:149], v[226:227], 0, s[14:15]
	s_mov_b32 m0, s62
	s_nop 0
	global_load_lds_dwordx4 v[148:149], off
	v_lshl_add_u64 v[148:149], v[228:229], 0, s[14:15]
	s_mov_b32 m0, s63
	s_nop 0
	global_load_lds_dwordx4 v[148:149], off
	s_waitcnt vmcnt(8)
	s_waitcnt lgkmcnt(0)
	s_setprio 1
	s_barrier
	v_mfma_f32_16x16x32_bf16 v[58:61], v[160:163], v[192:195], v[58:61]
	v_mfma_f32_16x16x32_bf16 v[50:53], v[168:171], v[192:195], v[50:53]
	v_mfma_f32_16x16x32_bf16 v[42:45], v[160:163], v[200:203], v[42:45]
	v_mfma_f32_16x16x32_bf16 v[34:37], v[168:171], v[200:203], v[34:37]
	v_mfma_f32_16x16x32_bf16 v[26:29], v[160:163], v[208:211], v[26:29]
	v_mfma_f32_16x16x32_bf16 v[18:21], v[168:171], v[208:211], v[18:21]
	v_mfma_f32_16x16x32_bf16 v[10:13], v[160:163], v[216:219], v[10:13]
	v_mfma_f32_16x16x32_bf16 v[6:9], v[168:171], v[216:219], v[6:9]
	v_mfma_f32_16x16x32_bf16 v[58:61], v[164:167], v[196:199], v[58:61]
	v_mfma_f32_16x16x32_bf16 v[50:53], v[172:175], v[196:199], v[50:53]
	v_mfma_f32_16x16x32_bf16 v[42:45], v[164:167], v[204:207], v[42:45]
	v_mfma_f32_16x16x32_bf16 v[34:37], v[172:175], v[204:207], v[34:37]
	v_mfma_f32_16x16x32_bf16 v[26:29], v[164:167], v[212:215], v[26:29]
	v_mfma_f32_16x16x32_bf16 v[18:21], v[172:175], v[212:215], v[18:21]
	v_mfma_f32_16x16x32_bf16 v[10:13], v[164:167], v[220:223], v[10:13]
	v_mfma_f32_16x16x32_bf16 v[6:9], v[172:175], v[220:223], v[6:9]
	s_setprio 0
	s_setprio 1
	v_mfma_f32_16x16x32_bf16 v[62:65], v[176:179], v[192:195], v[62:65]
	v_mfma_f32_16x16x32_bf16 v[54:57], v[184:187], v[192:195], v[54:57]
	v_mfma_f32_16x16x32_bf16 v[46:49], v[176:179], v[200:203], v[46:49]
	v_mfma_f32_16x16x32_bf16 v[38:41], v[184:187], v[200:203], v[38:41]
	v_mfma_f32_16x16x32_bf16 v[30:33], v[176:179], v[208:211], v[30:33]
	v_mfma_f32_16x16x32_bf16 v[22:25], v[184:187], v[208:211], v[22:25]
	v_mfma_f32_16x16x32_bf16 v[14:17], v[176:179], v[216:219], v[14:17]
	v_mfma_f32_16x16x32_bf16 v[2:5], v[184:187], v[216:219], v[2:5]
	v_mfma_f32_16x16x32_bf16 v[62:65], v[180:183], v[196:199], v[62:65]
	v_mfma_f32_16x16x32_bf16 v[54:57], v[188:191], v[196:199], v[54:57]
	v_mfma_f32_16x16x32_bf16 v[46:49], v[180:183], v[204:207], v[46:49]
	v_mfma_f32_16x16x32_bf16 v[38:41], v[188:191], v[204:207], v[38:41]
	v_mfma_f32_16x16x32_bf16 v[30:33], v[180:183], v[212:215], v[30:33]
	v_mfma_f32_16x16x32_bf16 v[22:25], v[188:191], v[212:215], v[22:25]
	v_mfma_f32_16x16x32_bf16 v[14:17], v[180:183], v[220:223], v[14:17]
	v_mfma_f32_16x16x32_bf16 v[2:5], v[188:191], v[220:223], v[2:5]
	s_setprio 0
	s_barrier
	s_add_i32 s73, s73, 2
	s_add_u32 s48, s48, 0x100
	s_addc_u32 s49, s49, 0
	s_add_u32 s71, s71, 0x100
	s_addc_u32 s72, s72, 0
	s_cmp_gt_u32 s73, 13
	s_cbranch_scc0 .LBB0_840
	s_branch .Lz_post_p6

.Lz_post_p6:
	s_lshl_b32 s25, s46, 8
	v_add_u32_e32 v148, s25, v150
	v_ashrrev_i32_e32 v149, 31, v148
	v_lshl_add_u64 v[244:245], v[148:149], 2, s[10:11]
	global_load_dword v149, v[244:245], off
	global_load_dword v232, v[244:245], off offset:64
	global_load_dword v233, v[244:245], off offset:128
	global_load_dword v234, v[244:245], off offset:192
	global_load_dword v235, v[244:245], off offset:512
	global_load_dword v236, v[244:245], off offset:576
	global_load_dword v237, v[244:245], off offset:640
	global_load_dword v238, v[244:245], off offset:704
	v_pk_mul_f32 v[128:129], v[120:121], v[128:129]
	v_pk_mul_f32 v[126:127], v[118:119], v[126:127]
	v_pk_mul_f32 v[124:125], v[116:117], v[124:125]
	v_pk_mul_f32 v[244:245], v[114:115], v[122:123]
	v_add_u32_e32 v246, s25, v152
	s_lshl_b32 s46, s47, 7
	v_mov_b64_e32 v[122:123], s[12:13]
	s_ashr_i32 s47, s46, 31
	v_mad_i64_i32 v[248:249], s[48:49], v148, s68, v[122:123]
	s_lshl_b64 s[46:47], s[46:47], 1
	v_lshl_add_u64 v[248:249], v[248:249], 0, s[46:47]
	v_lshl_add_u64 v[248:249], v[248:249], 0, v[138:139]
	v_pk_mul_f32 v[112:113], v[108:109], v[112:113]
	v_pk_mul_f32 v[110:111], v[106:107], v[110:111]
	v_pk_mul_f32 v[104:105], v[100:101], v[104:105]
	v_pk_mul_f32 v[102:103], v[98:99], v[102:103]
	v_pk_mul_f32 v[96:97], v[92:93], v[96:97]
	v_pk_mul_f32 v[94:95], v[90:91], v[94:95]
	v_pk_mul_f32 v[88:89], v[84:85], v[88:89]
	v_pk_mul_f32 v[86:87], v[82:83], v[86:87]
	v_pk_mul_f32 v[80:81], v[76:77], v[80:81]
	v_pk_mul_f32 v[78:79], v[74:75], v[78:79]
	v_pk_mul_f32 v[72:73], v[68:69], v[72:73]
	v_pk_mul_f32 v[70:71], v[66:67], v[70:71]
	v_pk_mul_f32 v[64:65], v[60:61], v[64:65]
	v_pk_mul_f32 v[62:63], v[58:59], v[62:63]
	v_pk_mul_f32 v[56:57], v[52:53], v[56:57]
	v_pk_mul_f32 v[54:55], v[50:51], v[54:55]
	v_pk_mul_f32 v[48:49], v[44:45], v[48:49]
	v_pk_mul_f32 v[46:47], v[42:43], v[46:47]
	v_pk_mul_f32 v[40:41], v[36:37], v[40:41]
	v_pk_mul_f32 v[38:39], v[34:35], v[38:39]
	v_pk_mul_f32 v[32:33], v[28:29], v[32:33]
	v_pk_mul_f32 v[30:31], v[26:27], v[30:31]
	v_pk_mul_f32 v[24:25], v[20:21], v[24:25]
	v_pk_mul_f32 v[22:23], v[18:19], v[22:23]
	v_pk_mul_f32 v[16:17], v[12:13], v[16:17]
	v_pk_mul_f32 v[14:15], v[10:11], v[14:15]
	v_pk_mul_f32 v[4:5], v[8:9], v[4:5]
	v_pk_mul_f32 v[2:3], v[6:7], v[2:3]
	s_and_b64 vcc, exec, s[16:17]
	s_cbranch_vccz .LBB0_843
	s_barrier
.LBB0_843:
	ds_read_b128 v[160:163], v155
	ds_read_b128 v[164:167], v155 offset:1024
	ds_read_b128 v[168:171], v155 offset:2048
	ds_read_b128 v[172:175], v155 offset:3072
	ds_read_b128 v[176:179], v156
	ds_read_b128 v[180:183], v156 offset:1024
	ds_read_b128 v[184:187], v156 offset:2048
	ds_read_b128 v[188:191], v156 offset:3072
	ds_read_b128 v[192:195], v157
	ds_read_b128 v[196:199], v157 offset:1024
	ds_read_b128 v[200:203], v157 offset:2048
	ds_read_b128 v[204:207], v157 offset:3072
	ds_read_b128 v[208:211], v157 offset:4096
	ds_read_b128 v[212:215], v157 offset:5120
	ds_read_b128 v[216:219], v157 offset:6144
	ds_read_b128 v[220:223], v157 offset:7168
	s_andn2_b64 vcc, exec, s[4:5]
	s_waitcnt vmcnt(0)
	v_fmamk_f32 v239, v149, 0x3a800000, v158
	v_rsq_f32_e32 v149, v239
	s_nop 0
	v_mul_f32_e32 v252, 0xbfb8aa3b, v149
	v_pk_mul_f32 v[120:121], v[120:121], v[252:253] op_sel_hi:[1,0]
	v_pk_mul_f32 v[118:119], v[118:119], v[252:253] op_sel_hi:[1,0]
	v_pk_mul_f32 v[116:117], v[116:117], v[252:253] op_sel_hi:[1,0]
	v_pk_mul_f32 v[114:115], v[114:115], v[252:253] op_sel_hi:[1,0]
	v_exp_f32_e32 v118, v118
	v_exp_f32_e32 v119, v119
	v_exp_f32_e32 v120, v120
	v_exp_f32_e32 v121, v121
	v_exp_f32_e32 v114, v114
	v_exp_f32_e32 v115, v115
	v_exp_f32_e32 v116, v116
	v_exp_f32_e32 v117, v117
	v_fma_f32 v118, v118, v239, v239
	v_fma_f32 v119, v119, v239, v239
	v_fma_f32 v120, v120, v239, v239
	v_fma_f32 v121, v121, v239, v239
	v_fma_f32 v149, v114, v239, v239
	v_fma_f32 v159, v115, v239, v239
	v_fma_f32 v247, v116, v239, v239
	v_fma_f32 v252, v117, v239, v239
	v_rcp_f32_e32 v114, v118
	v_rcp_f32_e32 v115, v119
	v_rcp_f32_e32 v116, v120
	v_rcp_f32_e32 v117, v121
	v_rcp_f32_e32 v118, v149
	v_rcp_f32_e32 v119, v159
	v_rcp_f32_e32 v120, v247
	v_rcp_f32_e32 v121, v252
	v_pk_mul_f32 v[116:117], v[128:129], v[116:117]
	v_pk_mul_f32 v[114:115], v[126:127], v[114:115]
	v_pk_mul_f32 v[120:121], v[124:125], v[120:121]
	v_pk_mul_f32 v[118:119], v[244:245], v[118:119]
	v_cvt_pk_bf16_f32 v114, v114, v115
	v_cvt_pk_bf16_f32 v115, v116, v117
	v_cvt_pk_bf16_f32 v116, v118, v119
	v_cvt_pk_bf16_f32 v117, v120, v121
	global_store_dwordx4 v[248:249], v[114:117], off
	v_fmamk_f32 v239, v232, 0x3a800000, v158
	v_rsq_f32_e32 v121, v239
	v_add_u32_e32 v114, s25, v153
	v_mul_f32_e32 v120, 0xbfb8aa3b, v121
	v_pk_mul_f32 v[108:109], v[108:109], v[120:121] op_sel_hi:[1,0]
	v_pk_mul_f32 v[106:107], v[106:107], v[120:121] op_sel_hi:[1,0]
	v_pk_mul_f32 v[100:101], v[100:101], v[120:121] op_sel_hi:[1,0]
	v_pk_mul_f32 v[98:99], v[98:99], v[120:121] op_sel_hi:[1,0]
	v_exp_f32_e32 v106, v106
	v_exp_f32_e32 v107, v107
	v_exp_f32_e32 v108, v108
	v_exp_f32_e32 v109, v109
	v_exp_f32_e32 v98, v98
	v_exp_f32_e32 v99, v99
	v_exp_f32_e32 v100, v100
	v_exp_f32_e32 v101, v101
	v_fma_f32 v106, v106, v239, v239
	v_fma_f32 v107, v107, v239, v239
	v_fma_f32 v108, v108, v239, v239
	v_fma_f32 v109, v109, v239, v239
	v_fma_f32 v115, v98, v239, v239
	v_fma_f32 v120, v99, v239, v239
	v_fma_f32 v121, v100, v239, v239
	v_fma_f32 v125, v101, v239, v239
	v_rcp_f32_e32 v98, v106
	v_rcp_f32_e32 v99, v107
	v_rcp_f32_e32 v100, v108
	v_rcp_f32_e32 v101, v109
	v_rcp_f32_e32 v106, v115
	v_rcp_f32_e32 v107, v120
	v_rcp_f32_e32 v108, v121
	v_rcp_f32_e32 v109, v125
	v_mad_i64_i32 v[116:117], s[48:49], v246, s68, v[122:123]
	v_lshl_add_u64 v[116:117], v[116:117], 0, s[46:47]
	v_pk_mul_f32 v[100:101], v[112:113], v[100:101]
	v_pk_mul_f32 v[98:99], v[110:111], v[98:99]
	v_pk_mul_f32 v[104:105], v[104:105], v[108:109]
	v_pk_mul_f32 v[102:103], v[102:103], v[106:107]
	v_lshl_add_u64 v[116:117], v[116:117], 0, v[138:139]
	v_cvt_pk_bf16_f32 v98, v98, v99
	v_cvt_pk_bf16_f32 v99, v100, v101
	v_cvt_pk_bf16_f32 v100, v102, v103
	v_cvt_pk_bf16_f32 v101, v104, v105
	global_store_dwordx4 v[116:117], v[98:101], off
	v_fmamk_f32 v239, v233, 0x3a800000, v158
	v_rsq_f32_e32 v105, v239
	v_add_u32_e32 v98, s25, v154
	v_mul_f32_e32 v104, 0xbfb8aa3b, v105
	v_pk_mul_f32 v[92:93], v[92:93], v[104:105] op_sel_hi:[1,0]
	v_pk_mul_f32 v[90:91], v[90:91], v[104:105] op_sel_hi:[1,0]
	v_pk_mul_f32 v[84:85], v[84:85], v[104:105] op_sel_hi:[1,0]
	v_pk_mul_f32 v[82:83], v[82:83], v[104:105] op_sel_hi:[1,0]
	v_exp_f32_e32 v90, v90
	v_exp_f32_e32 v91, v91
	v_exp_f32_e32 v92, v92
	v_exp_f32_e32 v93, v93
	v_exp_f32_e32 v82, v82
	v_exp_f32_e32 v83, v83
	v_exp_f32_e32 v84, v84
	v_exp_f32_e32 v85, v85
	v_fma_f32 v90, v90, v239, v239
	v_fma_f32 v91, v91, v239, v239
	v_fma_f32 v92, v92, v239, v239
	v_fma_f32 v93, v93, v239, v239
	v_fma_f32 v99, v82, v239, v239
	v_fma_f32 v104, v83, v239, v239
	v_fma_f32 v105, v84, v239, v239
	v_fma_f32 v107, v85, v239, v239
	v_rcp_f32_e32 v82, v90
	v_rcp_f32_e32 v83, v91
	v_rcp_f32_e32 v84, v92
	v_rcp_f32_e32 v85, v93
	v_rcp_f32_e32 v90, v99
	v_rcp_f32_e32 v91, v104
	v_rcp_f32_e32 v92, v105
	v_rcp_f32_e32 v93, v107
	v_mad_i64_i32 v[100:101], s[48:49], v114, s68, v[122:123]
	v_lshl_add_u64 v[100:101], v[100:101], 0, s[46:47]
	v_pk_mul_f32 v[84:85], v[96:97], v[84:85]
	v_pk_mul_f32 v[82:83], v[94:95], v[82:83]
	v_pk_mul_f32 v[88:89], v[88:89], v[92:93]
	v_pk_mul_f32 v[86:87], v[86:87], v[90:91]
	v_lshl_add_u64 v[100:101], v[100:101], 0, v[138:139]
	v_cvt_pk_bf16_f32 v82, v82, v83
	v_cvt_pk_bf16_f32 v83, v84, v85
	v_cvt_pk_bf16_f32 v84, v86, v87
	v_cvt_pk_bf16_f32 v85, v88, v89
	global_store_dwordx4 v[100:101], v[82:85], off
	s_nop 0
	s_nop 0
	v_add_u32_e32 v84, 0x80, v148
	v_mad_i64_i32 v[82:83], s[48:49], v98, s68, v[122:123]
	v_lshl_add_u64 v[82:83], v[82:83], 0, s[46:47]
	v_lshl_add_u64 v[82:83], v[82:83], 0, v[138:139]
	v_fmamk_f32 v239, v234, 0x3a800000, v158
	v_rsq_f32_e32 v89, v239
	s_nop 0
	v_mul_f32_e32 v88, 0xbfb8aa3b, v89
	v_pk_mul_f32 v[76:77], v[76:77], v[88:89] op_sel_hi:[1,0]
	v_pk_mul_f32 v[74:75], v[74:75], v[88:89] op_sel_hi:[1,0]
	v_pk_mul_f32 v[68:69], v[68:69], v[88:89] op_sel_hi:[1,0]
	v_pk_mul_f32 v[66:67], v[66:67], v[88:89] op_sel_hi:[1,0]
	v_exp_f32_e32 v74, v74
	v_exp_f32_e32 v75, v75
	v_exp_f32_e32 v76, v76
	v_exp_f32_e32 v77, v77
	v_exp_f32_e32 v66, v66
	v_exp_f32_e32 v67, v67
	v_exp_f32_e32 v68, v68
	v_exp_f32_e32 v69, v69
	v_fma_f32 v74, v74, v239, v239
	v_fma_f32 v75, v75, v239, v239
	v_fma_f32 v76, v76, v239, v239
	v_fma_f32 v77, v77, v239, v239
	v_fma_f32 v85, v66, v239, v239
	v_fma_f32 v88, v67, v239, v239
	v_fma_f32 v89, v68, v239, v239
	v_fma_f32 v91, v69, v239, v239
	v_rcp_f32_e32 v66, v74
	v_rcp_f32_e32 v67, v75
	v_rcp_f32_e32 v68, v76
	v_rcp_f32_e32 v69, v77
	v_rcp_f32_e32 v74, v85
	v_rcp_f32_e32 v75, v88
	v_rcp_f32_e32 v76, v89
	v_rcp_f32_e32 v77, v91
	v_pk_mul_f32 v[68:69], v[80:81], v[68:69]
	v_pk_mul_f32 v[66:67], v[78:79], v[66:67]
	v_pk_mul_f32 v[72:73], v[72:73], v[76:77]
	v_pk_mul_f32 v[70:71], v[70:71], v[74:75]
	v_cvt_pk_bf16_f32 v66, v66, v67
	v_cvt_pk_bf16_f32 v67, v68, v69
	v_cvt_pk_bf16_f32 v68, v70, v71
	v_cvt_pk_bf16_f32 v69, v72, v73
	global_store_dwordx4 v[82:83], v[66:69], off
	v_fmamk_f32 v239, v235, 0x3a800000, v158
	v_rsq_f32_e32 v73, v239
	v_add_u32_e32 v66, 0x90, v148
	v_mul_f32_e32 v72, 0xbfb8aa3b, v73
	v_pk_mul_f32 v[60:61], v[60:61], v[72:73] op_sel_hi:[1,0]
	v_pk_mul_f32 v[58:59], v[58:59], v[72:73] op_sel_hi:[1,0]
	v_pk_mul_f32 v[52:53], v[52:53], v[72:73] op_sel_hi:[1,0]
	v_pk_mul_f32 v[50:51], v[50:51], v[72:73] op_sel_hi:[1,0]
	v_exp_f32_e32 v58, v58
	v_exp_f32_e32 v59, v59
	v_exp_f32_e32 v60, v60
	v_exp_f32_e32 v61, v61
	v_exp_f32_e32 v50, v50
	v_exp_f32_e32 v51, v51
	v_exp_f32_e32 v52, v52
	v_exp_f32_e32 v53, v53
	v_fma_f32 v58, v58, v239, v239
	v_fma_f32 v59, v59, v239, v239
	v_fma_f32 v60, v60, v239, v239
	v_fma_f32 v61, v61, v239, v239
	v_fma_f32 v67, v50, v239, v239
	v_fma_f32 v72, v51, v239, v239
	v_fma_f32 v73, v52, v239, v239
	v_fma_f32 v75, v53, v239, v239
	v_rcp_f32_e32 v50, v58
	v_rcp_f32_e32 v51, v59
	v_rcp_f32_e32 v52, v60
	v_rcp_f32_e32 v53, v61
	v_rcp_f32_e32 v58, v67
	v_rcp_f32_e32 v59, v72
	v_rcp_f32_e32 v60, v73
	v_rcp_f32_e32 v61, v75
	v_mad_i64_i32 v[68:69], s[48:49], v84, s68, v[122:123]
	v_lshl_add_u64 v[68:69], v[68:69], 0, s[46:47]
	v_pk_mul_f32 v[52:53], v[64:65], v[52:53]
	v_pk_mul_f32 v[50:51], v[62:63], v[50:51]
	v_pk_mul_f32 v[56:57], v[56:57], v[60:61]
	v_pk_mul_f32 v[54:55], v[54:55], v[58:59]
	v_lshl_add_u64 v[68:69], v[68:69], 0, v[138:139]
	v_cvt_pk_bf16_f32 v50, v50, v51
	v_cvt_pk_bf16_f32 v51, v52, v53
	v_cvt_pk_bf16_f32 v52, v54, v55
	v_cvt_pk_bf16_f32 v53, v56, v57
	global_store_dwordx4 v[68:69], v[50:53], off
	v_fmamk_f32 v239, v236, 0x3a800000, v158
	v_rsq_f32_e32 v57, v239
	v_add_u32_e32 v50, 0xa0, v148
	v_mul_f32_e32 v56, 0xbfb8aa3b, v57
	v_pk_mul_f32 v[44:45], v[44:45], v[56:57] op_sel_hi:[1,0]
	v_pk_mul_f32 v[42:43], v[42:43], v[56:57] op_sel_hi:[1,0]
	v_pk_mul_f32 v[36:37], v[36:37], v[56:57] op_sel_hi:[1,0]
	v_pk_mul_f32 v[34:35], v[34:35], v[56:57] op_sel_hi:[1,0]
	v_exp_f32_e32 v42, v42
	v_exp_f32_e32 v43, v43
	v_exp_f32_e32 v44, v44
	v_exp_f32_e32 v45, v45
	v_exp_f32_e32 v34, v34
	v_exp_f32_e32 v35, v35
	v_exp_f32_e32 v36, v36
	v_exp_f32_e32 v37, v37
	v_fma_f32 v42, v42, v239, v239
	v_fma_f32 v43, v43, v239, v239
	v_fma_f32 v44, v44, v239, v239
	v_fma_f32 v45, v45, v239, v239
	v_fma_f32 v51, v34, v239, v239
	v_fma_f32 v56, v35, v239, v239
	v_fma_f32 v57, v36, v239, v239
	v_fma_f32 v59, v37, v239, v239
	v_rcp_f32_e32 v34, v42
	v_rcp_f32_e32 v35, v43
	v_rcp_f32_e32 v36, v44
	v_rcp_f32_e32 v37, v45
	v_rcp_f32_e32 v42, v51
	v_rcp_f32_e32 v43, v56
	v_rcp_f32_e32 v44, v57
	v_rcp_f32_e32 v45, v59
	v_mad_i64_i32 v[52:53], s[48:49], v66, s68, v[122:123]
	v_lshl_add_u64 v[52:53], v[52:53], 0, s[46:47]
	v_pk_mul_f32 v[36:37], v[48:49], v[36:37]
	v_pk_mul_f32 v[34:35], v[46:47], v[34:35]
	v_pk_mul_f32 v[40:41], v[40:41], v[44:45]
	v_pk_mul_f32 v[38:39], v[38:39], v[42:43]
	v_lshl_add_u64 v[52:53], v[52:53], 0, v[138:139]
	v_cvt_pk_bf16_f32 v34, v34, v35
	v_cvt_pk_bf16_f32 v35, v36, v37
	v_cvt_pk_bf16_f32 v36, v38, v39
	v_cvt_pk_bf16_f32 v37, v40, v41
	global_store_dwordx4 v[52:53], v[34:37], off
	v_fmamk_f32 v239, v237, 0x3a800000, v158
	v_rsq_f32_e32 v41, v239
	v_add_u32_e32 v34, 0xb0, v148
	v_mul_f32_e32 v40, 0xbfb8aa3b, v41
	v_pk_mul_f32 v[28:29], v[28:29], v[40:41] op_sel_hi:[1,0]
	v_pk_mul_f32 v[26:27], v[26:27], v[40:41] op_sel_hi:[1,0]
	v_pk_mul_f32 v[20:21], v[20:21], v[40:41] op_sel_hi:[1,0]
	v_pk_mul_f32 v[18:19], v[18:19], v[40:41] op_sel_hi:[1,0]
	v_exp_f32_e32 v26, v26
	v_exp_f32_e32 v27, v27
	v_exp_f32_e32 v28, v28
	v_exp_f32_e32 v29, v29
	v_exp_f32_e32 v18, v18
	v_exp_f32_e32 v19, v19
	v_exp_f32_e32 v20, v20
	v_exp_f32_e32 v21, v21
	v_fma_f32 v26, v26, v239, v239
	v_fma_f32 v27, v27, v239, v239
	v_fma_f32 v28, v28, v239, v239
	v_fma_f32 v29, v29, v239, v239
	v_fma_f32 v35, v18, v239, v239
	v_fma_f32 v40, v19, v239, v239
	v_fma_f32 v41, v20, v239, v239
	v_fma_f32 v43, v21, v239, v239
	v_rcp_f32_e32 v18, v26
	v_rcp_f32_e32 v19, v27
	v_rcp_f32_e32 v20, v28
	v_rcp_f32_e32 v21, v29
	v_rcp_f32_e32 v26, v35
	v_rcp_f32_e32 v27, v40
	v_rcp_f32_e32 v28, v41
	v_rcp_f32_e32 v29, v43
	v_mad_i64_i32 v[36:37], s[48:49], v50, s68, v[122:123]
	v_lshl_add_u64 v[36:37], v[36:37], 0, s[46:47]
	v_pk_mul_f32 v[20:21], v[32:33], v[20:21]
	v_pk_mul_f32 v[18:19], v[30:31], v[18:19]
	v_pk_mul_f32 v[24:25], v[24:25], v[28:29]
	v_pk_mul_f32 v[22:23], v[22:23], v[26:27]
	v_lshl_add_u64 v[36:37], v[36:37], 0, v[138:139]
	v_cvt_pk_bf16_f32 v18, v18, v19
	v_cvt_pk_bf16_f32 v19, v20, v21
	v_cvt_pk_bf16_f32 v20, v22, v23
	v_cvt_pk_bf16_f32 v21, v24, v25
	global_store_dwordx4 v[36:37], v[18:21], off
	s_nop 0
	s_nop 0
	v_fmamk_f32 v239, v238, 0x3a800000, v158
	v_rsq_f32_e32 v21, v239
	v_mad_i64_i32 v[18:19], s[4:5], v34, s68, v[122:123]
	v_lshl_add_u64 v[18:19], v[18:19], 0, s[46:47]
	v_mul_f32_e32 v20, 0xbfb8aa3b, v21
	v_pk_mul_f32 v[12:13], v[12:13], v[20:21] op_sel_hi:[1,0]
	v_pk_mul_f32 v[10:11], v[10:11], v[20:21] op_sel_hi:[1,0]
	v_pk_mul_f32 v[8:9], v[8:9], v[20:21] op_sel_hi:[1,0]
	v_pk_mul_f32 v[6:7], v[6:7], v[20:21] op_sel_hi:[1,0]
	v_exp_f32_e32 v10, v10
	v_exp_f32_e32 v11, v11
	v_exp_f32_e32 v12, v12
	v_exp_f32_e32 v13, v13
	v_exp_f32_e32 v6, v6
	v_exp_f32_e32 v7, v7
	v_exp_f32_e32 v8, v8
	v_exp_f32_e32 v9, v9
	v_fma_f32 v10, v10, v239, v239
	v_fma_f32 v11, v11, v239, v239
	v_fma_f32 v12, v12, v239, v239
	v_fma_f32 v13, v13, v239, v239
	v_fma_f32 v20, v6, v239, v239
	v_fma_f32 v21, v7, v239, v239
	v_fma_f32 v23, v8, v239, v239
	v_fma_f32 v24, v9, v239, v239
	v_rcp_f32_e32 v6, v10
	v_rcp_f32_e32 v7, v11
	v_rcp_f32_e32 v8, v12
	v_rcp_f32_e32 v9, v13
	v_rcp_f32_e32 v10, v20
	v_rcp_f32_e32 v11, v21
	v_rcp_f32_e32 v12, v23
	v_rcp_f32_e32 v13, v24
	v_pk_mul_f32 v[8:9], v[16:17], v[8:9]
	v_pk_mul_f32 v[6:7], v[14:15], v[6:7]
	v_pk_mul_f32 v[12:13], v[4:5], v[12:13]
	v_pk_mul_f32 v[4:5], v[2:3], v[10:11]
	v_lshl_add_u64 v[18:19], v[18:19], 0, v[138:139]
	v_cvt_pk_bf16_f32 v2, v6, v7
	v_cvt_pk_bf16_f32 v3, v8, v9
	v_cvt_pk_bf16_f32 v4, v4, v5
	v_cvt_pk_bf16_f32 v5, v12, v13
	s_mov_b64 s[4:5], -1
	global_store_dwordx4 v[18:19], v[2:5], off
	s_cbranch_vccnz .LBB0_836
	s_andn2_b64 vcc, exec, s[8:9]
	s_cbranch_vccnz .LBB0_835
	s_barrier
	s_branch .LBB0_835

.LBB0_1124:
	s_waitcnt lgkmcnt(0)
	s_add_u32 s8, s8, 0x60000
	s_addc_u32 s9, s9, 0
	s_add_u32 s10, s4, 0xa400000
	s_addc_u32 s11, s5, 0
	s_lshl_b32 s4, s14, 5
	s_mov_b64 s[14:15], 0x80
	s_and_b32 s26, s4, 0x60
	s_add_i32 m0, s57, 0x18000
	v_lshl_add_u64 v[8:9], v[8:9], 0, s[14:15]
	s_lshl_b32 s25, s24, 13
	s_lshl_b32 s27, s26, 7
	s_waitcnt vmcnt(2)
	s_barrier
	global_load_lds_dwordx4 v[8:9], off
	v_lshl_add_u64 v[6:7], v[6:7], 0, s[14:15]
	s_add_i32 m0, s57, 0x1a000
	s_add_i32 s62, s57, 0x8000
	s_add_i32 s63, s57, 0xa000
	global_load_lds_dwordx4 v[6:7], off
	v_lshl_add_u64 v[2:3], v[2:3], 0, s[14:15]
	s_mov_b32 m0, s62
	s_add_u32 s4, s50, 0x40080
	global_load_lds_dwordx4 v[2:3], off
	v_lshl_add_u64 v[2:3], v[4:5], 0, s[14:15]
	s_mov_b32 m0, s63
	s_addc_u32 s5, s51, 0
	global_load_lds_dwordx4 v[2:3], off
	s_add_i32 m0, s57, 0x1c000
	v_lshl_add_u64 v[2:3], s[4:5], 0, v[134:135]
	global_load_lds_dwordx4 v[2:3], off
	v_lshl_add_u64 v[2:3], s[4:5], 0, v[130:131]
	s_add_i32 m0, s57, 0x1e000
	s_cmpk_lt_u32 s17, 0x100
	global_load_lds_dwordx4 v[2:3], off
	v_lshrrev_b32_e32 v3, 1, v10
	v_and_b32_e32 v3, 24, v3
	v_and_b32_e32 v2, 15, v10
	v_lshlrev_b32_e32 v4, 1, v3
	v_lshl_or_b32 v150, s24, 6, v2
	v_lshl_or_b32 v2, v2, 6, v4
	v_lshlrev_b32_e32 v4, 2, v10
	v_and_b32_e32 v4, 32, v4
	v_bitop3_b32 v5, v2, s25, v4 bitop3:0xde
	v_bitop3_b32 v151, v2, s27, v4 bitop3:0xde
	v_or_b32_e32 v2, s26, v3
	v_lshlrev_b32_e32 v3, 14, v15
	v_and_b32_e32 v3, 0xffff8000, v3
	v_lshl_add_u32 v3, v14, 11, v3
	v_and_b32_e32 v4, 1, v15
	v_lshl_or_b32 v3, v4, 6, v3
	v_lshl_add_u32 v140, v16, 1, v3
	v_lshlrev_b32_e32 v3, 14, v11
	v_and_b32_e32 v3, 0xffff8000, v3
	s_waitcnt vmcnt(6)
	v_lshl_add_u32 v3, v12, 11, v3
	v_and_b32_e32 v4, 1, v11
	s_sext_i32_i16 s47, s16
	s_cselect_b64 s[16:17], -1, 0
	v_lshl_or_b32 v3, v4, 6, v3
	s_add_i32 s66, 0, 0x10000
	s_add_i32 s67, 0, 0x14000
	v_or_b32_e32 v152, 16, v150
	v_or_b32_e32 v153, 32, v150
	v_or_b32_e32 v154, 48, v150
	s_ashr_i32 s64, s38, 31
	s_mov_b32 s65, s38
	v_mov_b32_e32 v141, v139
	v_lshl_add_u32 v142, v13, 1, v3
	v_mov_b32_e32 v143, v139
	v_mov_b64_e32 v[144:145], 0xb00
	v_mov_b64_e32 v[146:147], 0xaff
	v_add_u32_e32 v155, s66, v151
	v_add_u32_e32 v156, s67, v151
	v_add_u32_e32 v157, 0, v5
	v_mov_b32_e32 v158, 0x358637bd
	s_movk_i32 s68, 0x1600
	v_lshlrev_b32_e32 v138, 1, v2
	s_barrier
	ds_read_b128 v[160:163], v155
	ds_read_b128 v[164:167], v155 offset:1024
	ds_read_b128 v[168:171], v155 offset:2048
	ds_read_b128 v[172:175], v155 offset:3072
	ds_read_b128 v[176:179], v156
	ds_read_b128 v[180:183], v156 offset:1024
	ds_read_b128 v[184:187], v156 offset:2048
	ds_read_b128 v[188:191], v156 offset:3072
	ds_read_b128 v[192:195], v157
	ds_read_b128 v[196:199], v157 offset:1024
	ds_read_b128 v[200:203], v157 offset:2048
	ds_read_b128 v[204:207], v157 offset:3072
	ds_read_b128 v[208:211], v157 offset:4096
	ds_read_b128 v[212:215], v157 offset:5120
	ds_read_b128 v[216:219], v157 offset:6144
	ds_read_b128 v[220:223], v157 offset:7168
	s_branch .LBB0_1127

.Lz_post_p8b:
	s_lshl_b32 s25, s46, 8
	v_add_u32_e32 v148, s25, v150
	v_ashrrev_i32_e32 v149, 31, v148
	v_lshl_add_u64 v[244:245], v[148:149], 2, s[8:9]
	global_load_dword v149, v[244:245], off
	global_load_dword v232, v[244:245], off offset:64
	global_load_dword v233, v[244:245], off offset:128
	global_load_dword v234, v[244:245], off offset:192
	global_load_dword v235, v[244:245], off offset:512
	global_load_dword v236, v[244:245], off offset:576
	global_load_dword v237, v[244:245], off offset:640
	global_load_dword v238, v[244:245], off offset:704
	v_pk_mul_f32 v[128:129], v[120:121], v[128:129]
	v_pk_mul_f32 v[126:127], v[118:119], v[126:127]
	v_pk_mul_f32 v[124:125], v[116:117], v[124:125]
	v_pk_mul_f32 v[244:245], v[114:115], v[122:123]
	v_add_u32_e32 v246, s25, v152
	s_lshl_b32 s46, s47, 7
	v_mov_b64_e32 v[122:123], s[10:11]
	s_ashr_i32 s47, s46, 31
	v_mad_i64_i32 v[248:249], s[48:49], v148, s68, v[122:123]
	s_lshl_b64 s[46:47], s[46:47], 1
	v_lshl_add_u64 v[248:249], v[248:249], 0, s[46:47]
	v_lshl_add_u64 v[248:249], v[248:249], 0, v[138:139]
	v_pk_mul_f32 v[112:113], v[108:109], v[112:113]
	v_pk_mul_f32 v[110:111], v[106:107], v[110:111]
	v_pk_mul_f32 v[104:105], v[100:101], v[104:105]
	v_pk_mul_f32 v[102:103], v[98:99], v[102:103]
	v_pk_mul_f32 v[96:97], v[92:93], v[96:97]
	v_pk_mul_f32 v[94:95], v[90:91], v[94:95]
	v_pk_mul_f32 v[88:89], v[84:85], v[88:89]
	v_pk_mul_f32 v[86:87], v[82:83], v[86:87]
	v_pk_mul_f32 v[80:81], v[76:77], v[80:81]
	v_pk_mul_f32 v[78:79], v[74:75], v[78:79]
	v_pk_mul_f32 v[72:73], v[68:69], v[72:73]
	v_pk_mul_f32 v[70:71], v[66:67], v[70:71]
	v_pk_mul_f32 v[64:65], v[60:61], v[64:65]
	v_pk_mul_f32 v[62:63], v[58:59], v[62:63]
	v_pk_mul_f32 v[56:57], v[52:53], v[56:57]
	v_pk_mul_f32 v[54:55], v[50:51], v[54:55]
	v_pk_mul_f32 v[48:49], v[44:45], v[48:49]
	v_pk_mul_f32 v[46:47], v[42:43], v[46:47]
	v_pk_mul_f32 v[40:41], v[36:37], v[40:41]
	v_pk_mul_f32 v[38:39], v[34:35], v[38:39]
	v_pk_mul_f32 v[32:33], v[28:29], v[32:33]
	v_pk_mul_f32 v[30:31], v[26:27], v[30:31]
	v_pk_mul_f32 v[24:25], v[20:21], v[24:25]
	v_pk_mul_f32 v[22:23], v[18:19], v[22:23]
	v_pk_mul_f32 v[16:17], v[12:13], v[16:17]
	v_pk_mul_f32 v[14:15], v[10:11], v[14:15]
	v_pk_mul_f32 v[4:5], v[8:9], v[4:5]
	v_pk_mul_f32 v[2:3], v[6:7], v[2:3]
	s_and_b64 vcc, exec, s[16:17]
	s_cbranch_vccz .LBB0_1133
	s_barrier
.LBB0_1133:
	ds_read_b128 v[160:163], v155
	ds_read_b128 v[164:167], v155 offset:1024
	ds_read_b128 v[168:171], v155 offset:2048
	ds_read_b128 v[172:175], v155 offset:3072
	ds_read_b128 v[176:179], v156
	ds_read_b128 v[180:183], v156 offset:1024
	ds_read_b128 v[184:187], v156 offset:2048
	ds_read_b128 v[188:191], v156 offset:3072
	ds_read_b128 v[192:195], v157
	ds_read_b128 v[196:199], v157 offset:1024
	ds_read_b128 v[200:203], v157 offset:2048
	ds_read_b128 v[204:207], v157 offset:3072
	ds_read_b128 v[208:211], v157 offset:4096
	ds_read_b128 v[212:215], v157 offset:5120
	ds_read_b128 v[216:219], v157 offset:6144
	ds_read_b128 v[220:223], v157 offset:7168
	s_andn2_b64 vcc, exec, s[4:5]
	s_waitcnt vmcnt(0)
	v_fmamk_f32 v239, v149, 0x3a800000, v158
	v_rsq_f32_e32 v149, v239
	s_nop 0
	v_mul_f32_e32 v252, 0xbfb8aa3b, v149
	v_pk_mul_f32 v[120:121], v[120:121], v[252:253] op_sel_hi:[1,0]
	v_pk_mul_f32 v[118:119], v[118:119], v[252:253] op_sel_hi:[1,0]
	v_pk_mul_f32 v[116:117], v[116:117], v[252:253] op_sel_hi:[1,0]
	v_pk_mul_f32 v[114:115], v[114:115], v[252:253] op_sel_hi:[1,0]
	v_exp_f32_e32 v118, v118
	v_exp_f32_e32 v119, v119
	v_exp_f32_e32 v120, v120
	v_exp_f32_e32 v121, v121
	v_exp_f32_e32 v114, v114
	v_exp_f32_e32 v115, v115
	v_exp_f32_e32 v116, v116
	v_exp_f32_e32 v117, v117
	v_fma_f32 v118, v118, v239, v239
	v_fma_f32 v119, v119, v239, v239
	v_fma_f32 v120, v120, v239, v239
	v_fma_f32 v121, v121, v239, v239
	v_fma_f32 v149, v114, v239, v239
	v_fma_f32 v159, v115, v239, v239
	v_fma_f32 v247, v116, v239, v239
	v_fma_f32 v252, v117, v239, v239
	v_rcp_f32_e32 v114, v118
	v_rcp_f32_e32 v115, v119
	v_rcp_f32_e32 v116, v120
	v_rcp_f32_e32 v117, v121
	v_rcp_f32_e32 v118, v149
	v_rcp_f32_e32 v119, v159
	v_rcp_f32_e32 v120, v247
	v_rcp_f32_e32 v121, v252
	v_pk_mul_f32 v[116:117], v[128:129], v[116:117]
	v_pk_mul_f32 v[114:115], v[126:127], v[114:115]
	v_pk_mul_f32 v[120:121], v[124:125], v[120:121]
	v_pk_mul_f32 v[118:119], v[244:245], v[118:119]
	v_cvt_pk_bf16_f32 v114, v114, v115
	v_cvt_pk_bf16_f32 v115, v116, v117
	v_cvt_pk_bf16_f32 v116, v118, v119
	v_cvt_pk_bf16_f32 v117, v120, v121
	global_store_dwordx4 v[248:249], v[114:117], off
	v_fmamk_f32 v239, v232, 0x3a800000, v158
	v_rsq_f32_e32 v121, v239
	v_add_u32_e32 v114, s25, v153
	v_mul_f32_e32 v120, 0xbfb8aa3b, v121
	v_pk_mul_f32 v[108:109], v[108:109], v[120:121] op_sel_hi:[1,0]
	v_pk_mul_f32 v[106:107], v[106:107], v[120:121] op_sel_hi:[1,0]
	v_pk_mul_f32 v[100:101], v[100:101], v[120:121] op_sel_hi:[1,0]
	v_pk_mul_f32 v[98:99], v[98:99], v[120:121] op_sel_hi:[1,0]
	v_exp_f32_e32 v106, v106
	v_exp_f32_e32 v107, v107
	v_exp_f32_e32 v108, v108
	v_exp_f32_e32 v109, v109
	v_exp_f32_e32 v98, v98
	v_exp_f32_e32 v99, v99
	v_exp_f32_e32 v100, v100
	v_exp_f32_e32 v101, v101
	v_fma_f32 v106, v106, v239, v239
	v_fma_f32 v107, v107, v239, v239
	v_fma_f32 v108, v108, v239, v239
	v_fma_f32 v109, v109, v239, v239
	v_fma_f32 v115, v98, v239, v239
	v_fma_f32 v120, v99, v239, v239
	v_fma_f32 v121, v100, v239, v239
	v_fma_f32 v125, v101, v239, v239
	v_rcp_f32_e32 v98, v106
	v_rcp_f32_e32 v99, v107
	v_rcp_f32_e32 v100, v108
	v_rcp_f32_e32 v101, v109
	v_rcp_f32_e32 v106, v115
	v_rcp_f32_e32 v107, v120
	v_rcp_f32_e32 v108, v121
	v_rcp_f32_e32 v109, v125
	v_mad_i64_i32 v[116:117], s[48:49], v246, s68, v[122:123]
	v_lshl_add_u64 v[116:117], v[116:117], 0, s[46:47]
	v_pk_mul_f32 v[100:101], v[112:113], v[100:101]
	v_pk_mul_f32 v[98:99], v[110:111], v[98:99]
	v_pk_mul_f32 v[104:105], v[104:105], v[108:109]
	v_pk_mul_f32 v[102:103], v[102:103], v[106:107]
	v_lshl_add_u64 v[116:117], v[116:117], 0, v[138:139]
	v_cvt_pk_bf16_f32 v98, v98, v99
	v_cvt_pk_bf16_f32 v99, v100, v101
	v_cvt_pk_bf16_f32 v100, v102, v103
	v_cvt_pk_bf16_f32 v101, v104, v105
	global_store_dwordx4 v[116:117], v[98:101], off
	v_fmamk_f32 v239, v233, 0x3a800000, v158
	v_rsq_f32_e32 v105, v239
	v_add_u32_e32 v98, s25, v154
	v_mul_f32_e32 v104, 0xbfb8aa3b, v105
	v_pk_mul_f32 v[92:93], v[92:93], v[104:105] op_sel_hi:[1,0]
	v_pk_mul_f32 v[90:91], v[90:91], v[104:105] op_sel_hi:[1,0]
	v_pk_mul_f32 v[84:85], v[84:85], v[104:105] op_sel_hi:[1,0]
	v_pk_mul_f32 v[82:83], v[82:83], v[104:105] op_sel_hi:[1,0]
	v_exp_f32_e32 v90, v90
	v_exp_f32_e32 v91, v91
	v_exp_f32_e32 v92, v92
	v_exp_f32_e32 v93, v93
	v_exp_f32_e32 v82, v82
	v_exp_f32_e32 v83, v83
	v_exp_f32_e32 v84, v84
	v_exp_f32_e32 v85, v85
	v_fma_f32 v90, v90, v239, v239
	v_fma_f32 v91, v91, v239, v239
	v_fma_f32 v92, v92, v239, v239
	v_fma_f32 v93, v93, v239, v239
	v_fma_f32 v99, v82, v239, v239
	v_fma_f32 v104, v83, v239, v239
	v_fma_f32 v105, v84, v239, v239
	v_fma_f32 v107, v85, v239, v239
	v_rcp_f32_e32 v82, v90
	v_rcp_f32_e32 v83, v91
	v_rcp_f32_e32 v84, v92
	v_rcp_f32_e32 v85, v93
	v_rcp_f32_e32 v90, v99
	v_rcp_f32_e32 v91, v104
	v_rcp_f32_e32 v92, v105
	v_rcp_f32_e32 v93, v107
	v_mad_i64_i32 v[100:101], s[48:49], v114, s68, v[122:123]
	v_lshl_add_u64 v[100:101], v[100:101], 0, s[46:47]
	v_pk_mul_f32 v[84:85], v[96:97], v[84:85]
	v_pk_mul_f32 v[82:83], v[94:95], v[82:83]
	v_pk_mul_f32 v[88:89], v[88:89], v[92:93]
	v_pk_mul_f32 v[86:87], v[86:87], v[90:91]
	v_lshl_add_u64 v[100:101], v[100:101], 0, v[138:139]
	v_cvt_pk_bf16_f32 v82, v82, v83
	v_cvt_pk_bf16_f32 v83, v84, v85
	v_cvt_pk_bf16_f32 v84, v86, v87
	v_cvt_pk_bf16_f32 v85, v88, v89
	global_store_dwordx4 v[100:101], v[82:85], off
	s_nop 0
	s_nop 0
	v_add_u32_e32 v84, 0x80, v148
	v_mad_i64_i32 v[82:83], s[48:49], v98, s68, v[122:123]
	v_lshl_add_u64 v[82:83], v[82:83], 0, s[46:47]
	v_lshl_add_u64 v[82:83], v[82:83], 0, v[138:139]
	v_fmamk_f32 v239, v234, 0x3a800000, v158
	v_rsq_f32_e32 v89, v239
	s_nop 0
	v_mul_f32_e32 v88, 0xbfb8aa3b, v89
	v_pk_mul_f32 v[76:77], v[76:77], v[88:89] op_sel_hi:[1,0]
	v_pk_mul_f32 v[74:75], v[74:75], v[88:89] op_sel_hi:[1,0]
	v_pk_mul_f32 v[68:69], v[68:69], v[88:89] op_sel_hi:[1,0]
	v_pk_mul_f32 v[66:67], v[66:67], v[88:89] op_sel_hi:[1,0]
	v_exp_f32_e32 v74, v74
	v_exp_f32_e32 v75, v75
	v_exp_f32_e32 v76, v76
	v_exp_f32_e32 v77, v77
	v_exp_f32_e32 v66, v66
	v_exp_f32_e32 v67, v67
	v_exp_f32_e32 v68, v68
	v_exp_f32_e32 v69, v69
	v_fma_f32 v74, v74, v239, v239
	v_fma_f32 v75, v75, v239, v239
	v_fma_f32 v76, v76, v239, v239
	v_fma_f32 v77, v77, v239, v239
	v_fma_f32 v85, v66, v239, v239
	v_fma_f32 v88, v67, v239, v239
	v_fma_f32 v89, v68, v239, v239
	v_fma_f32 v91, v69, v239, v239
	v_rcp_f32_e32 v66, v74
	v_rcp_f32_e32 v67, v75
	v_rcp_f32_e32 v68, v76
	v_rcp_f32_e32 v69, v77
	v_rcp_f32_e32 v74, v85
	v_rcp_f32_e32 v75, v88
	v_rcp_f32_e32 v76, v89
	v_rcp_f32_e32 v77, v91
	v_pk_mul_f32 v[68:69], v[80:81], v[68:69]
	v_pk_mul_f32 v[66:67], v[78:79], v[66:67]
	v_pk_mul_f32 v[72:73], v[72:73], v[76:77]
	v_pk_mul_f32 v[70:71], v[70:71], v[74:75]
	v_cvt_pk_bf16_f32 v66, v66, v67
	v_cvt_pk_bf16_f32 v67, v68, v69
	v_cvt_pk_bf16_f32 v68, v70, v71
	v_cvt_pk_bf16_f32 v69, v72, v73
	global_store_dwordx4 v[82:83], v[66:69], off
	v_fmamk_f32 v239, v235, 0x3a800000, v158
	v_rsq_f32_e32 v73, v239
	v_add_u32_e32 v66, 0x90, v148
	v_mul_f32_e32 v72, 0xbfb8aa3b, v73
	v_pk_mul_f32 v[60:61], v[60:61], v[72:73] op_sel_hi:[1,0]
	v_pk_mul_f32 v[58:59], v[58:59], v[72:73] op_sel_hi:[1,0]
	v_pk_mul_f32 v[52:53], v[52:53], v[72:73] op_sel_hi:[1,0]
	v_pk_mul_f32 v[50:51], v[50:51], v[72:73] op_sel_hi:[1,0]
	v_exp_f32_e32 v58, v58
	v_exp_f32_e32 v59, v59
	v_exp_f32_e32 v60, v60
	v_exp_f32_e32 v61, v61
	v_exp_f32_e32 v50, v50
	v_exp_f32_e32 v51, v51
	v_exp_f32_e32 v52, v52
	v_exp_f32_e32 v53, v53
	v_fma_f32 v58, v58, v239, v239
	v_fma_f32 v59, v59, v239, v239
	v_fma_f32 v60, v60, v239, v239
	v_fma_f32 v61, v61, v239, v239
	v_fma_f32 v67, v50, v239, v239
	v_fma_f32 v72, v51, v239, v239
	v_fma_f32 v73, v52, v239, v239
	v_fma_f32 v75, v53, v239, v239
	v_rcp_f32_e32 v50, v58
	v_rcp_f32_e32 v51, v59
	v_rcp_f32_e32 v52, v60
	v_rcp_f32_e32 v53, v61
	v_rcp_f32_e32 v58, v67
	v_rcp_f32_e32 v59, v72
	v_rcp_f32_e32 v60, v73
	v_rcp_f32_e32 v61, v75
	v_mad_i64_i32 v[68:69], s[48:49], v84, s68, v[122:123]
	v_lshl_add_u64 v[68:69], v[68:69], 0, s[46:47]
	v_pk_mul_f32 v[52:53], v[64:65], v[52:53]
	v_pk_mul_f32 v[50:51], v[62:63], v[50:51]
	v_pk_mul_f32 v[56:57], v[56:57], v[60:61]
	v_pk_mul_f32 v[54:55], v[54:55], v[58:59]
	v_lshl_add_u64 v[68:69], v[68:69], 0, v[138:139]
	v_cvt_pk_bf16_f32 v50, v50, v51
	v_cvt_pk_bf16_f32 v51, v52, v53
	v_cvt_pk_bf16_f32 v52, v54, v55
	v_cvt_pk_bf16_f32 v53, v56, v57
	global_store_dwordx4 v[68:69], v[50:53], off
	v_fmamk_f32 v239, v236, 0x3a800000, v158
	v_rsq_f32_e32 v57, v239
	v_add_u32_e32 v50, 0xa0, v148
	v_mul_f32_e32 v56, 0xbfb8aa3b, v57
	v_pk_mul_f32 v[44:45], v[44:45], v[56:57] op_sel_hi:[1,0]
	v_pk_mul_f32 v[42:43], v[42:43], v[56:57] op_sel_hi:[1,0]
	v_pk_mul_f32 v[36:37], v[36:37], v[56:57] op_sel_hi:[1,0]
	v_pk_mul_f32 v[34:35], v[34:35], v[56:57] op_sel_hi:[1,0]
	v_exp_f32_e32 v42, v42
	v_exp_f32_e32 v43, v43
	v_exp_f32_e32 v44, v44
	v_exp_f32_e32 v45, v45
	v_exp_f32_e32 v34, v34
	v_exp_f32_e32 v35, v35
	v_exp_f32_e32 v36, v36
	v_exp_f32_e32 v37, v37
	v_fma_f32 v42, v42, v239, v239
	v_fma_f32 v43, v43, v239, v239
	v_fma_f32 v44, v44, v239, v239
	v_fma_f32 v45, v45, v239, v239
	v_fma_f32 v51, v34, v239, v239
	v_fma_f32 v56, v35, v239, v239
	v_fma_f32 v57, v36, v239, v239
	v_fma_f32 v59, v37, v239, v239
	v_rcp_f32_e32 v34, v42
	v_rcp_f32_e32 v35, v43
	v_rcp_f32_e32 v36, v44
	v_rcp_f32_e32 v37, v45
	v_rcp_f32_e32 v42, v51
	v_rcp_f32_e32 v43, v56
	v_rcp_f32_e32 v44, v57
	v_rcp_f32_e32 v45, v59
	v_mad_i64_i32 v[52:53], s[48:49], v66, s68, v[122:123]
	v_lshl_add_u64 v[52:53], v[52:53], 0, s[46:47]
	v_pk_mul_f32 v[36:37], v[48:49], v[36:37]
	v_pk_mul_f32 v[34:35], v[46:47], v[34:35]
	v_pk_mul_f32 v[40:41], v[40:41], v[44:45]
	v_pk_mul_f32 v[38:39], v[38:39], v[42:43]
	v_lshl_add_u64 v[52:53], v[52:53], 0, v[138:139]
	v_cvt_pk_bf16_f32 v34, v34, v35
	v_cvt_pk_bf16_f32 v35, v36, v37
	v_cvt_pk_bf16_f32 v36, v38, v39
	v_cvt_pk_bf16_f32 v37, v40, v41
	global_store_dwordx4 v[52:53], v[34:37], off
	v_fmamk_f32 v239, v237, 0x3a800000, v158
	v_rsq_f32_e32 v41, v239
	v_add_u32_e32 v34, 0xb0, v148
	v_mul_f32_e32 v40, 0xbfb8aa3b, v41
	v_pk_mul_f32 v[28:29], v[28:29], v[40:41] op_sel_hi:[1,0]
	v_pk_mul_f32 v[26:27], v[26:27], v[40:41] op_sel_hi:[1,0]
	v_pk_mul_f32 v[20:21], v[20:21], v[40:41] op_sel_hi:[1,0]
	v_pk_mul_f32 v[18:19], v[18:19], v[40:41] op_sel_hi:[1,0]
	v_exp_f32_e32 v26, v26
	v_exp_f32_e32 v27, v27
	v_exp_f32_e32 v28, v28
	v_exp_f32_e32 v29, v29
	v_exp_f32_e32 v18, v18
	v_exp_f32_e32 v19, v19
	v_exp_f32_e32 v20, v20
	v_exp_f32_e32 v21, v21
	v_fma_f32 v26, v26, v239, v239
	v_fma_f32 v27, v27, v239, v239
	v_fma_f32 v28, v28, v239, v239
	v_fma_f32 v29, v29, v239, v239
	v_fma_f32 v35, v18, v239, v239
	v_fma_f32 v40, v19, v239, v239
	v_fma_f32 v41, v20, v239, v239
	v_fma_f32 v43, v21, v239, v239
	v_rcp_f32_e32 v18, v26
	v_rcp_f32_e32 v19, v27
	v_rcp_f32_e32 v20, v28
	v_rcp_f32_e32 v21, v29
	v_rcp_f32_e32 v26, v35
	v_rcp_f32_e32 v27, v40
	v_rcp_f32_e32 v28, v41
	v_rcp_f32_e32 v29, v43
	v_mad_i64_i32 v[36:37], s[48:49], v50, s68, v[122:123]
	v_lshl_add_u64 v[36:37], v[36:37], 0, s[46:47]
	v_pk_mul_f32 v[20:21], v[32:33], v[20:21]
	v_pk_mul_f32 v[18:19], v[30:31], v[18:19]
	v_pk_mul_f32 v[24:25], v[24:25], v[28:29]
	v_pk_mul_f32 v[22:23], v[22:23], v[26:27]
	v_lshl_add_u64 v[36:37], v[36:37], 0, v[138:139]
	v_cvt_pk_bf16_f32 v18, v18, v19
	v_cvt_pk_bf16_f32 v19, v20, v21
	v_cvt_pk_bf16_f32 v20, v22, v23
	v_cvt_pk_bf16_f32 v21, v24, v25
	global_store_dwordx4 v[36:37], v[18:21], off
	s_nop 0
	s_nop 0
	v_fmamk_f32 v239, v238, 0x3a800000, v158
	v_rsq_f32_e32 v21, v239
	v_mad_i64_i32 v[18:19], s[4:5], v34, s68, v[122:123]
	v_lshl_add_u64 v[18:19], v[18:19], 0, s[46:47]
	v_mul_f32_e32 v20, 0xbfb8aa3b, v21
	v_pk_mul_f32 v[12:13], v[12:13], v[20:21] op_sel_hi:[1,0]
	v_pk_mul_f32 v[10:11], v[10:11], v[20:21] op_sel_hi:[1,0]
	v_pk_mul_f32 v[8:9], v[8:9], v[20:21] op_sel_hi:[1,0]
	v_pk_mul_f32 v[6:7], v[6:7], v[20:21] op_sel_hi:[1,0]
	v_exp_f32_e32 v10, v10
	v_exp_f32_e32 v11, v11
	v_exp_f32_e32 v12, v12
	v_exp_f32_e32 v13, v13
	v_exp_f32_e32 v6, v6
	v_exp_f32_e32 v7, v7
	v_exp_f32_e32 v8, v8
	v_exp_f32_e32 v9, v9
	v_fma_f32 v10, v10, v239, v239
	v_fma_f32 v11, v11, v239, v239
	v_fma_f32 v12, v12, v239, v239
	v_fma_f32 v13, v13, v239, v239
	v_fma_f32 v20, v6, v239, v239
	v_fma_f32 v21, v7, v239, v239
	v_fma_f32 v23, v8, v239, v239
	v_fma_f32 v24, v9, v239, v239
	v_rcp_f32_e32 v6, v10
	v_rcp_f32_e32 v7, v11
	v_rcp_f32_e32 v8, v12
	v_rcp_f32_e32 v9, v13
	v_rcp_f32_e32 v10, v20
	v_rcp_f32_e32 v11, v21
	v_rcp_f32_e32 v12, v23
	v_rcp_f32_e32 v13, v24
	v_pk_mul_f32 v[8:9], v[16:17], v[8:9]
	v_pk_mul_f32 v[6:7], v[14:15], v[6:7]
	v_pk_mul_f32 v[12:13], v[4:5], v[12:13]
	v_pk_mul_f32 v[4:5], v[2:3], v[10:11]
	v_lshl_add_u64 v[18:19], v[18:19], 0, v[138:139]
	v_cvt_pk_bf16_f32 v2, v6, v7
	v_cvt_pk_bf16_f32 v3, v8, v9
	v_cvt_pk_bf16_f32 v4, v4, v5
	v_cvt_pk_bf16_f32 v5, v12, v13
	s_mov_b64 s[4:5], -1
	global_store_dwordx4 v[18:19], v[2:5], off
	s_cbranch_vccnz .LBB0_1126
	s_andn2_b64 vcc, exec, s[6:7]
	s_cbranch_vccnz .LBB0_1125
	s_barrier
	s_branch .LBB0_1125

.LBB0_1804:
	s_waitcnt lgkmcnt(0)
	s_add_u32 s10, s10, 0xe0000
	s_addc_u32 s11, s11, 0
	s_add_u32 s12, s4, 0xa400000
	s_addc_u32 s13, s5, 0
	s_lshl_b32 s4, s14, 5
	s_mov_b64 s[14:15], 0x80
	s_and_b32 s26, s4, 0x60
	s_add_i32 m0, s57, 0x18000
	v_lshl_add_u64 v[8:9], v[8:9], 0, s[14:15]
	s_lshl_b32 s25, s24, 13
	s_lshl_b32 s27, s26, 7
	s_waitcnt vmcnt(2)
	s_barrier
	global_load_lds_dwordx4 v[8:9], off
	v_lshl_add_u64 v[6:7], v[6:7], 0, s[14:15]
	s_add_i32 m0, s57, 0x1a000
	s_add_i32 s62, s57, 0x8000
	s_add_i32 s63, s57, 0xa000
	global_load_lds_dwordx4 v[6:7], off
	v_lshl_add_u64 v[2:3], v[2:3], 0, s[14:15]
	s_mov_b32 m0, s62
	s_add_u32 s4, s50, 0x40080
	global_load_lds_dwordx4 v[2:3], off
	v_lshl_add_u64 v[2:3], v[4:5], 0, s[14:15]
	s_mov_b32 m0, s63
	s_addc_u32 s5, s51, 0
	global_load_lds_dwordx4 v[2:3], off
	s_add_i32 m0, s57, 0x1c000
	v_lshl_add_u64 v[2:3], s[4:5], 0, v[134:135]
	global_load_lds_dwordx4 v[2:3], off
	v_lshl_add_u64 v[2:3], s[4:5], 0, v[130:131]
	s_add_i32 m0, s57, 0x1e000
	s_cmpk_lt_u32 s17, 0x100
	global_load_lds_dwordx4 v[2:3], off
	v_lshrrev_b32_e32 v3, 1, v10
	v_and_b32_e32 v3, 24, v3
	v_and_b32_e32 v2, 15, v10
	v_lshlrev_b32_e32 v4, 1, v3
	v_lshl_or_b32 v150, s24, 6, v2
	v_lshl_or_b32 v2, v2, 6, v4
	v_lshlrev_b32_e32 v4, 2, v10
	v_and_b32_e32 v4, 32, v4
	v_bitop3_b32 v5, v2, s25, v4 bitop3:0xde
	v_bitop3_b32 v151, v2, s27, v4 bitop3:0xde
	v_or_b32_e32 v2, s26, v3
	v_lshlrev_b32_e32 v3, 14, v15
	v_and_b32_e32 v3, 0xffff8000, v3
	v_lshl_add_u32 v3, v14, 11, v3
	v_and_b32_e32 v4, 1, v15
	v_lshl_or_b32 v3, v4, 6, v3
	v_lshl_add_u32 v140, v16, 1, v3
	v_lshlrev_b32_e32 v3, 14, v11
	v_and_b32_e32 v3, 0xffff8000, v3
	s_waitcnt vmcnt(6)
	v_lshl_add_u32 v3, v12, 11, v3
	v_and_b32_e32 v4, 1, v11
	s_sext_i32_i16 s47, s16
	s_cselect_b64 s[16:17], -1, 0
	v_lshl_or_b32 v3, v4, 6, v3
	s_add_i32 s66, 0, 0x10000
	s_add_i32 s67, 0, 0x14000
	v_or_b32_e32 v152, 16, v150
	v_or_b32_e32 v153, 32, v150
	v_or_b32_e32 v154, 48, v150
	s_ashr_i32 s64, s38, 31
	s_mov_b32 s65, s38
	v_mov_b32_e32 v141, v139
	v_lshl_add_u32 v142, v13, 1, v3
	v_mov_b32_e32 v143, v139
	v_mov_b64_e32 v[144:145], 0xb00
	v_mov_b64_e32 v[146:147], 0xaff
	v_add_u32_e32 v155, s66, v151
	v_add_u32_e32 v156, s67, v151
	v_add_u32_e32 v157, 0, v5
	v_mov_b32_e32 v158, 0x358637bd
	s_movk_i32 s68, 0x1600
	v_lshlrev_b32_e32 v138, 1, v2
	s_barrier
	ds_read_b128 v[160:163], v155
	ds_read_b128 v[164:167], v155 offset:1024
	ds_read_b128 v[168:171], v155 offset:2048
	ds_read_b128 v[172:175], v155 offset:3072
	ds_read_b128 v[176:179], v156
	ds_read_b128 v[180:183], v156 offset:1024
	ds_read_b128 v[184:187], v156 offset:2048
	ds_read_b128 v[188:191], v156 offset:3072
	ds_read_b128 v[192:195], v157
	ds_read_b128 v[196:199], v157 offset:1024
	ds_read_b128 v[200:203], v157 offset:2048
	ds_read_b128 v[204:207], v157 offset:3072
	ds_read_b128 v[208:211], v157 offset:4096
	ds_read_b128 v[212:215], v157 offset:5120
	ds_read_b128 v[216:219], v157 offset:6144
	ds_read_b128 v[220:223], v157 offset:7168
	s_branch .LBB0_1807
